# baseline (speedup 1.0000x reference)
; template <int EPI, int PN>
; __device__ void gemm_phase(const Params& p, const u16* __restrict__ A, const u16* __restrict__ Bt, int nNt, char* smem) {
;     ...
;     for (int kt = 0; kt < 32; ++kt) {
;       asm volatile("s_waitcnt vmcnt(0)" ::: "memory");
;       __builtin_amdgcn_s_barrier();
;       const u16* Ab = ring + (kt & 1) * STG;
;       const u16* Bb = Ab + 16384;
;       u16* st = ring + ((kt + 1) & 1) * STG;
;       const bool pre = (kt + 1 < 32);
;       s16x8 af[2][4], bf[2][2];
;       auto ldfrag = [&](int ks, int slot) {
; #pragma unroll
;         for (int i = 0; i < 4; ++i) {
;           const int row = wr * 128 + i * 32 + lr;
;           af[slot][i] = *(const s16x8*)(Ab + row * 64 + (((ks * 2 + lh) ^ ((row >> 1) & 7)) * 8));
;         }
; #pragma unroll
;         for (int j = 0; j < 2; ++j) {
;           const int rowb = nh * 128 + wc * 64 + j * 32 + lr;
;           bf[slot][j] = *(const s16x8*)(Bb + rowb * 64 + (((ks * 2 + lh) ^ ((rowb >> 1) & 7)) * 8));
;         }
;       };
;       ldfrag(0, 0);
;       ldfrag(1, 1);
;       __builtin_amdgcn_sched_barrier(0);
; #pragma unroll
;       for (int ks = 0; ks < 4; ++ks) {
;         const int slot = ks & 1;
; #pragma unroll
;         for (int i = 0; i < 4; ++i) {
;           acc[i][0] = mfma32(af[slot][i], bf[slot][0], acc[i][0]);
;           acc[i][1] = mfma32(af[slot][i], bf[slot][1], acc[i][1]);
;           __builtin_amdgcn_sched_barrier(0);
;           if (pre && (i & 1) == 0) {
;             const int pi = ks * 2 + (i >> 1);
;             if (pi < 4) glds16(Ag0 + (size_t)pi * 64 * LDK + (kt + 1) * 64, st + (srow + 64 * pi) * 64 + sch * 8);
;             else glds16(Bg0 + (size_t)(pi - 4) * 64 * LDK + (kt + 1) * 64, st + 16384 + (srow + 64 * (pi - 4)) * 64 + sch * 8);
;             __builtin_amdgcn_sched_barrier(0);
;           }
;         }
;         if (ks + 2 < 4) { ldfrag(ks + 2, slot); __builtin_amdgcn_sched_barrier(0); }
;       }
.Lrot129_loop:
	s_add_i32 s13, s12, 0xffff8000
	s_and_b32 s13, s13, 0x8000
	s_lshl_b32 s13, s13, 1
	v_lshl_or_b32 v128, v143, 1, s13
	v_lshl_add_u32 v149, v147, 1, s13
	s_and_b32 s98, s12, 0x8000
	s_lshl_b32 s98, s98, 1
	s_waitcnt lgkmcnt(7)
	v_mfma_f32_32x32x16_bf16 v[64:79], v[178:181], v[194:197], v[64:79]
	v_add3_u32 v226, s98, v162, v156
	s_waitcnt lgkmcnt(6)
	v_mfma_f32_32x32x16_bf16 v[112:127], v[178:181], v[198:201], v[112:127]
	v_readfirstlane_b32 s100, v226
	s_mov_b32 s20, m0
	s_add_i32 m0, s100, 0x8000
	s_nop 0
	global_load_lds_dwordx4 v[160:161], off
	v_mfma_f32_32x32x16_bf16 v[32:47], v[182:185], v[194:197], v[32:47]
	v_lshl_add_u64 v[178:179], v[160:161], 0, s[2:3]
	s_add_i32 m0, s100, 0xa000
	s_nop 0
	global_load_lds_dwordx4 v[178:179], off
	v_mfma_f32_32x32x16_bf16 v[96:111], v[182:185], v[198:201], v[96:111]
	v_lshl_add_u64 v[180:181], v[160:161], 0, s[4:5]
	s_add_i32 m0, s100, 0xc000
	s_nop 0
	global_load_lds_dwordx4 v[180:181], off
	v_mfma_f32_32x32x16_bf16 v[16:31], v[186:189], v[194:197], v[16:31]
	v_lshl_add_u64 v[178:179], v[160:161], 0, s[6:7]
	s_add_i32 m0, s100, 0xe000
	s_nop 0
	global_load_lds_dwordx4 v[178:179], off
	s_mov_b32 m0, s20
	v_mfma_f32_32x32x16_bf16 v[80:95], v[186:189], v[198:201], v[80:95]
	v_mfma_f32_32x32x16_bf16 v[0:15], v[190:193], v[194:197], v[0:15]
	v_mfma_f32_32x32x16_bf16 v[48:63], v[190:193], v[198:201], v[48:63]
	v_lshl_add_u64 v[160:161], v[160:161], 0, s[8:9]
	v_add_u32_e32 v177, v128, v175
	ds_read_b128 v[178:181], v177
	ds_read_b128 v[182:185], v177 offset:4096
	ds_read_b128 v[186:189], v177 offset:8192
	ds_read_b128 v[190:193], v177 offset:12288
	v_add_u32_e32 v177, v149, v175
	ds_read_b128 v[194:197], v177 offset:32768
	ds_read_b128 v[198:201], v177 offset:36864
	s_waitcnt lgkmcnt(7)
	v_mfma_f32_32x32x16_bf16 v[64:79], v[202:205], v[218:221], v[64:79]
	s_waitcnt lgkmcnt(6)
	v_mfma_f32_32x32x16_bf16 v[112:127], v[202:205], v[222:225], v[112:127]
	v_mfma_f32_32x32x16_bf16 v[32:47], v[206:209], v[218:221], v[32:47]
	v_mfma_f32_32x32x16_bf16 v[96:111], v[206:209], v[222:225], v[96:111]
	v_mfma_f32_32x32x16_bf16 v[16:31], v[210:213], v[218:221], v[16:31]
	v_mfma_f32_32x32x16_bf16 v[80:95], v[210:213], v[222:225], v[80:95]
	v_mfma_f32_32x32x16_bf16 v[0:15], v[214:217], v[218:221], v[0:15]
	v_mfma_f32_32x32x16_bf16 v[48:63], v[214:217], v[222:225], v[48:63]
	v_add_u32_e32 v128, v128, v176
	ds_read_b128 v[202:205], v128
	ds_read_b128 v[206:209], v128 offset:4096
	ds_read_b128 v[210:213], v128 offset:8192
	ds_read_b128 v[214:217], v128 offset:12288
	v_add_u32_e32 v128, v149, v176
	ds_read_b128 v[218:221], v128 offset:32768
	ds_read_b128 v[222:225], v128 offset:36864
	s_waitcnt lgkmcnt(7)
	v_mfma_f32_32x32x16_bf16 v[64:79], v[178:181], v[194:197], v[64:79]
	s_waitcnt lgkmcnt(6)
	v_mfma_f32_32x32x16_bf16 v[112:127], v[178:181], v[198:201], v[112:127]
	v_mfma_f32_32x32x16_bf16 v[32:47], v[182:185], v[194:197], v[32:47]
	v_mfma_f32_32x32x16_bf16 v[96:111], v[182:185], v[198:201], v[96:111]
	v_mfma_f32_32x32x16_bf16 v[16:31], v[186:189], v[194:197], v[16:31]
	v_mfma_f32_32x32x16_bf16 v[80:95], v[186:189], v[198:201], v[80:95]
	v_mfma_f32_32x32x16_bf16 v[0:15], v[190:193], v[194:197], v[0:15]
	v_mfma_f32_32x32x16_bf16 v[48:63], v[190:193], v[198:201], v[48:63]
	v_lshl_or_b32 v227, v143, 1, s98
	v_lshl_add_u32 v229, v147, 1, s98
	v_add_u32_e32 v228, v227, v173
	v_add_u32_e32 v230, v229, v173
	s_waitcnt vmcnt(0) lgkmcnt(0)
	s_barrier
	ds_read_b128 v[178:181], v228
	ds_read_b128 v[182:185], v228 offset:4096
	ds_read_b128 v[186:189], v228 offset:8192
	ds_read_b128 v[190:193], v228 offset:12288
	ds_read_b128 v[194:197], v230 offset:32768
	ds_read_b128 v[198:201], v230 offset:36864
	v_add3_u32 v226, s13, v162, v156
	v_mfma_f32_32x32x16_bf16 v[64:79], v[202:205], v[218:221], v[64:79]
	v_readfirstlane_b32 s99, v226
	s_mov_b32 s20, m0
	s_mov_b32 m0, s99
	s_nop 0
	global_load_lds_dwordx4 v[158:159], off
	v_mfma_f32_32x32x16_bf16 v[112:127], v[202:205], v[222:225], v[112:127]
	v_lshl_add_u64 v[232:233], v[158:159], 0, s[2:3]
	s_add_i32 m0, s99, 0x2000
	s_nop 0
	global_load_lds_dwordx4 v[232:233], off
	v_mfma_f32_32x32x16_bf16 v[32:47], v[206:209], v[218:221], v[32:47]
	v_lshl_add_u64 v[234:235], v[158:159], 0, s[4:5]
	s_add_i32 m0, s99, 0x4000
	s_nop 0
	global_load_lds_dwordx4 v[234:235], off
	v_mfma_f32_32x32x16_bf16 v[96:111], v[206:209], v[222:225], v[96:111]
	v_lshl_add_u64 v[232:233], v[158:159], 0, s[6:7]
	s_add_i32 m0, s99, 0x6000
	s_nop 0
	global_load_lds_dwordx4 v[232:233], off
	s_mov_b32 m0, s20
	v_mfma_f32_32x32x16_bf16 v[16:31], v[210:213], v[218:221], v[16:31]
	v_mfma_f32_32x32x16_bf16 v[80:95], v[210:213], v[222:225], v[80:95]
	v_mfma_f32_32x32x16_bf16 v[0:15], v[214:217], v[218:221], v[0:15]
	v_mfma_f32_32x32x16_bf16 v[48:63], v[214:217], v[222:225], v[48:63]
	v_add_u32_e32 v228, v227, v174
	v_add_u32_e32 v230, v229, v174
	ds_read_b128 v[202:205], v228
	ds_read_b128 v[206:209], v228 offset:4096
	ds_read_b128 v[210:213], v228 offset:8192
	ds_read_b128 v[214:217], v228 offset:12288
	ds_read_b128 v[218:221], v230 offset:32768
	ds_read_b128 v[222:225], v230 offset:36864
	s_add_i32 s12, s12, 0x8000
	v_lshl_add_u64 v[158:159], v[158:159], 0, s[8:9]
	s_cmp_eq_u32 s12, 0xf8000
	s_cbranch_scc0 .Lrot129_loop
; template <int EPI, int PN>
; __device__ void gemm_phase(const Params& p, const u16* __restrict__ A, const u16* __restrict__ Bt, int nNt, char* smem) {
;     ...
;   for (int q = jb;; q += NJ) {
;     const int pl = q / (4 * PN), w = q % (4 * PN);
;     const int gp = pl * 8 + xcd;
;     if (gp >= npatch) break;
;     const int mt = (gp / npn) * 4 + (w & 3), nt = (gp % npn) * PN + (w >> 2);
;     const int gch = sch ^ ((srow >> 1) & 7);
;     const u16* Ag0 = A + (size_t)(mt * 256 + srow) * LDK + gch * 8;
;     const u16* Bg0 = Bt + (size_t)(nt * 256 + srow) * LDK + gch * 8;
;     ...
;     for (int kt = 0; kt < 32; ++kt) {
;       asm volatile("s_waitcnt vmcnt(0)" ::: "memory");
;       __builtin_amdgcn_s_barrier();
;       const u16* Ab = ring + (kt & 1) * STG;
;       const u16* Bb = Ab + 16384;
;       u16* st = ring + ((kt + 1) & 1) * STG;
;       const bool pre = (kt + 1 < 32);
;       s16x8 af[2][4], bf[2][2];
;       auto ldfrag = [&](int ks, int slot) {
; #pragma unroll
;         for (int i = 0; i < 4; ++i) {
;           const int row = wr * 128 + i * 32 + lr;
;           af[slot][i] = *(const s16x8*)(Ab + row * 64 + (((ks * 2 + lh) ^ ((row >> 1) & 7)) * 8));
;         }
; #pragma unroll
;         for (int j = 0; j < 2; ++j) {
;           const int rowb = nh * 128 + wc * 64 + j * 32 + lr;
;           bf[slot][j] = *(const s16x8*)(Bb + rowb * 64 + (((ks * 2 + lh) ^ ((rowb >> 1) & 7)) * 8));
;         }
;       };
;       ldfrag(0, 0);
;       ldfrag(1, 1);
;       __builtin_amdgcn_sched_barrier(0);
; #pragma unroll
;       for (int ks = 0; ks < 4; ++ks) {
;         const int slot = ks & 1;
; #pragma unroll
;         for (int i = 0; i < 4; ++i) {
;           acc[i][0] = mfma32(af[slot][i], bf[slot][0], acc[i][0]);
;           acc[i][1] = mfma32(af[slot][i], bf[slot][1], acc[i][1]);
;           __builtin_amdgcn_sched_barrier(0);
;           if (pre && (i & 1) == 0) {
;             const int pi = ks * 2 + (i >> 1);
;             if (pi < 4) glds16(Ag0 + (size_t)pi * 64 * LDK + (kt + 1) * 64, st + (srow + 64 * pi) * 64 + sch * 8);
;             else glds16(Bg0 + (size_t)(pi - 4) * 64 * LDK + (kt + 1) * 64, st + 16384 + (srow + 64 * (pi - 4)) * 64 + sch * 8);
;             __builtin_amdgcn_sched_barrier(0);
;           }
;         }
;         if (ks + 2 < 4) { ldfrag(ks + 2, slot); __builtin_amdgcn_sched_barrier(0); }
;       }
	s_add_i32 s13, s12, 0xffff8000
	s_and_b32 s13, s13, 0x8000
	s_lshl_b32 s13, s13, 1
	v_lshl_or_b32 v128, v143, 1, s13
	v_lshl_add_u32 v149, v147, 1, s13
	s_and_b32 s98, s12, 0x8000
	s_lshl_b32 s98, s98, 1
	s_waitcnt lgkmcnt(7)
	v_mfma_f32_32x32x16_bf16 v[64:79], v[178:181], v[194:197], v[64:79]
	v_add3_u32 v226, s98, v162, v156
	s_waitcnt lgkmcnt(6)
	v_mfma_f32_32x32x16_bf16 v[112:127], v[178:181], v[198:201], v[112:127]
	v_readfirstlane_b32 s100, v226
	s_mov_b32 s20, m0
	s_add_i32 m0, s100, 0x8000
	s_nop 0
	global_load_lds_dwordx4 v[160:161], off
	v_mfma_f32_32x32x16_bf16 v[32:47], v[182:185], v[194:197], v[32:47]
	v_lshl_add_u64 v[178:179], v[160:161], 0, s[2:3]
	s_add_i32 m0, s100, 0xa000
	s_nop 0
	global_load_lds_dwordx4 v[178:179], off
	v_mfma_f32_32x32x16_bf16 v[96:111], v[182:185], v[198:201], v[96:111]
	v_lshl_add_u64 v[180:181], v[160:161], 0, s[4:5]
	s_add_i32 m0, s100, 0xc000
	s_nop 0
	global_load_lds_dwordx4 v[180:181], off
	v_mfma_f32_32x32x16_bf16 v[16:31], v[186:189], v[194:197], v[16:31]
	v_lshl_add_u64 v[178:179], v[160:161], 0, s[6:7]
	s_add_i32 m0, s100, 0xe000
	s_nop 0
	global_load_lds_dwordx4 v[178:179], off
	s_mov_b32 m0, s20
	v_mfma_f32_32x32x16_bf16 v[80:95], v[186:189], v[198:201], v[80:95]
	v_mfma_f32_32x32x16_bf16 v[0:15], v[190:193], v[194:197], v[0:15]
	v_mfma_f32_32x32x16_bf16 v[48:63], v[190:193], v[198:201], v[48:63]
	v_lshl_add_u64 v[160:161], v[160:161], 0, s[8:9]
	v_add_u32_e32 v177, v128, v175
	ds_read_b128 v[178:181], v177
	ds_read_b128 v[182:185], v177 offset:4096
	ds_read_b128 v[186:189], v177 offset:8192
	ds_read_b128 v[190:193], v177 offset:12288
	v_add_u32_e32 v177, v149, v175
	ds_read_b128 v[194:197], v177 offset:32768
	ds_read_b128 v[198:201], v177 offset:36864
	s_waitcnt lgkmcnt(7)
	v_mfma_f32_32x32x16_bf16 v[64:79], v[202:205], v[218:221], v[64:79]
	s_waitcnt lgkmcnt(6)
	v_mfma_f32_32x32x16_bf16 v[112:127], v[202:205], v[222:225], v[112:127]
	v_mfma_f32_32x32x16_bf16 v[32:47], v[206:209], v[218:221], v[32:47]
	v_mfma_f32_32x32x16_bf16 v[96:111], v[206:209], v[222:225], v[96:111]
	v_mfma_f32_32x32x16_bf16 v[16:31], v[210:213], v[218:221], v[16:31]
	v_mfma_f32_32x32x16_bf16 v[80:95], v[210:213], v[222:225], v[80:95]
	v_mfma_f32_32x32x16_bf16 v[0:15], v[214:217], v[218:221], v[0:15]
	v_mfma_f32_32x32x16_bf16 v[48:63], v[214:217], v[222:225], v[48:63]
	v_add_u32_e32 v128, v128, v176
	ds_read_b128 v[202:205], v128
	ds_read_b128 v[206:209], v128 offset:4096
	ds_read_b128 v[210:213], v128 offset:8192
	ds_read_b128 v[214:217], v128 offset:12288
	v_add_u32_e32 v128, v149, v176
	ds_read_b128 v[218:221], v128 offset:32768
	ds_read_b128 v[222:225], v128 offset:36864
	v_readlane_b32 s98, v254, 28
	v_readlane_b32 s99, v254, 24
	s_nop 1
	s_add_i32 s98, s19, s98
	s_mul_hi_i32 s100, s98, 0xb21642c9
	s_add_i32 s100, s100, s98
	s_lshr_b32 s101, s100, 31
	s_ashr_i32 s100, s100, 6
	s_add_i32 s100, s100, s101
	s_lshl_b32 s101, s100, 3
	s_or_b32 s101, s101, s99
	s_cmp_lt_i32 s101, 32
	s_cselect_b32 s98, s98, s19
	s_mul_hi_i32 s100, s98, 0xb21642c9
	s_add_i32 s100, s100, s98
	s_lshr_b32 s101, s100, 31
	s_ashr_i32 s100, s100, 6
	s_add_i32 s100, s100, s101
	s_mul_i32 s101, s100, 0x5c
	s_sub_i32 s101, s98, s101
	s_lshl_b32 s100, s100, 3
	s_or_b32 s100, s100, s99
	s_and_b32 s99, s101, 3
	s_lshl_b32 s100, s100, 2
	s_or_b32 s100, s100, s99
	s_ashr_i32 s101, s101, 2
	v_lshrrev_b32_e32 v236, 6, v252
	v_and_b32_e32 v237, 3, v236
	v_lshl_add_u32 v237, v237, 6, v135
	v_mov_b32_e32 v238, s101
	v_mov_b32_e32 v239, s100
	v_cmp_gt_u32_e32 vcc, 4, v236
	v_readlane_b32 s98, v253, 29
	v_readlane_b32 s99, v253, 30
	v_readlane_b32 s100, v253, 31
	v_readlane_b32 s101, v253, 32
	v_cndmask_b32_e32 v238, v238, v239, vcc
	v_lshl_add_u32 v237, v238, 8, v237
	v_mov_b32_e32 v240, s100
	v_mov_b32_e32 v241, s101
	v_mov_b32_e32 v242, s98
	v_mov_b32_e32 v243, s99
	v_cndmask_b32_e32 v240, v240, v242, vcc
	v_cndmask_b32_e32 v241, v241, v243, vcc
	v_mad_u64_u32 v[240:241], s[98:99], v237, s0, v[240:241]
	global_load_dword v236, v[240:241], off
	global_load_dword v237, v[240:241], off offset:128
	global_load_dword v244, v[240:241], off offset:256
	global_load_dword v245, v[240:241], off offset:384
	s_waitcnt lgkmcnt(7)
	v_mfma_f32_32x32x16_bf16 v[64:79], v[178:181], v[194:197], v[64:79]
	s_waitcnt lgkmcnt(6)
	v_mfma_f32_32x32x16_bf16 v[112:127], v[178:181], v[198:201], v[112:127]
	v_mfma_f32_32x32x16_bf16 v[32:47], v[182:185], v[194:197], v[32:47]
	v_mfma_f32_32x32x16_bf16 v[96:111], v[182:185], v[198:201], v[96:111]
	v_mfma_f32_32x32x16_bf16 v[16:31], v[186:189], v[194:197], v[16:31]
	v_mfma_f32_32x32x16_bf16 v[80:95], v[186:189], v[198:201], v[80:95]
	v_mfma_f32_32x32x16_bf16 v[0:15], v[190:193], v[194:197], v[0:15]
	v_mfma_f32_32x32x16_bf16 v[48:63], v[190:193], v[198:201], v[48:63]
	s_waitcnt lgkmcnt(1)
	v_mfma_f32_32x32x16_bf16 v[64:79], v[202:205], v[218:221], v[64:79]
	s_waitcnt lgkmcnt(0)
	v_mfma_f32_32x32x16_bf16 v[112:127], v[202:205], v[222:225], v[112:127]
	v_mfma_f32_32x32x16_bf16 v[32:47], v[206:209], v[218:221], v[32:47]
	v_mfma_f32_32x32x16_bf16 v[96:111], v[206:209], v[222:225], v[96:111]
	v_mfma_f32_32x32x16_bf16 v[16:31], v[210:213], v[218:221], v[16:31]
	v_mfma_f32_32x32x16_bf16 v[80:95], v[210:213], v[222:225], v[80:95]
	v_mfma_f32_32x32x16_bf16 v[0:15], v[214:217], v[218:221], v[0:15]
	v_mfma_f32_32x32x16_bf16 v[48:63], v[214:217], v[222:225], v[48:63]
	s_waitcnt vmcnt(4)
	s_barrier
; __device__ __forceinline__ int accrow(int reg, int lh) { return (reg & 3) + 8 * (reg >> 2) + 4 * lh; }
; template <int EPI, int PN>
; __device__ void gemm_phase(const Params& p, const u16* __restrict__ A, const u16* __restrict__ Bt, int nNt, char* smem) {
;     ...
;       ldfrag(0, 0);
;       ldfrag(1, 1);
;       __builtin_amdgcn_sched_barrier(0);
; #pragma unroll
;       for (int ks = 0; ks < 4; ++ks) {
;         const int slot = ks & 1;
; #pragma unroll
;         for (int i = 0; i < 4; ++i) {
;           acc[i][0] = mfma32(af[slot][i], bf[slot][0], acc[i][0]);
;           acc[i][1] = mfma32(af[slot][i], bf[slot][1], acc[i][1]);
;           __builtin_amdgcn_sched_barrier(0);
;           if (pre && (i & 1) == 0) {
;             const int pi = ks * 2 + (i >> 1);
;             if (pi < 4) glds16(Ag0 + (size_t)pi * 64 * LDK + (kt + 1) * 64, st + (srow + 64 * pi) * 64 + sch * 8);
;             else glds16(Bg0 + (size_t)(pi - 4) * 64 * LDK + (kt + 1) * 64, st + 16384 + (srow + 64 * (pi - 4)) * 64 + sch * 8);
;             __builtin_amdgcn_sched_barrier(0);
;           }
;         }
;         if (ks + 2 < 4) { ldfrag(ks + 2, slot); __builtin_amdgcn_sched_barrier(0); }
;       }
;     }
;     __syncthreads();
;     ...
;     } else if (EPI == 0 && col0 >= NPROJ) {
; #pragma unroll
;       for (int i = 0; i < 4; ++i)
; #pragma unroll
;         for (int r = 0; r < 16; ++r) {
;           const size_t row = row0 + i * 32 + accrow(r, lhE);
;           const int col = col0 + lrE;
;           if (col < NIN) p.dtraw[row * 16 + (col - NPROJ)] = acc[i][0][r];
;         }
;     } else {
; #pragma unroll
;       for (int i = 0; i < 4; ++i)
; #pragma unroll
;         for (int j = 0; j < 2; ++j)
; #pragma unroll
;           for (int r = 0; r < 16; ++r) *(u16*)(et + (i * 32 + accrow(r, lhE)) * 144 + (j * 32 + lrE) * 2) = f2bf(acc[i][j][r]);
	ds_read_b128 v[158:161], v164
	ds_read_b128 v[178:181], v164 offset:4096
	ds_read_b128 v[182:185], v164 offset:8192
	ds_read_b128 v[186:189], v164 offset:12288
	ds_read_b128 v[190:193], v165
	ds_read_b128 v[194:197], v165 offset:4096
	ds_read_b128 v[198:201], v166
	ds_read_b128 v[202:205], v166 offset:4096
	ds_read_b128 v[206:209], v166 offset:8192
	ds_read_b128 v[210:213], v166 offset:12288
	ds_read_b128 v[214:217], v168
	ds_read_b128 v[218:221], v168 offset:4096
	s_waitcnt lgkmcnt(7)
	v_mfma_f32_32x32x16_bf16 v[64:79], v[158:161], v[190:193], v[64:79]
	s_waitcnt lgkmcnt(6)
	v_mfma_f32_32x32x16_bf16 v[112:127], v[158:161], v[194:197], v[112:127]
	v_mfma_f32_32x32x16_bf16 v[32:47], v[178:181], v[190:193], v[32:47]
	v_mfma_f32_32x32x16_bf16 v[96:111], v[178:181], v[194:197], v[96:111]
	v_mfma_f32_32x32x16_bf16 v[16:31], v[182:185], v[190:193], v[16:31]
	v_mfma_f32_32x32x16_bf16 v[80:95], v[182:185], v[194:197], v[80:95]
	v_mfma_f32_32x32x16_bf16 v[0:15], v[186:189], v[190:193], v[0:15]
	v_mfma_f32_32x32x16_bf16 v[48:63], v[186:189], v[194:197], v[48:63]
	ds_read_b128 v[158:161], v169
	ds_read_b128 v[178:181], v169 offset:4096
	ds_read_b128 v[182:185], v169 offset:8192
	ds_read_b128 v[186:189], v169 offset:12288
	ds_read_b128 v[190:193], v170
	ds_read_b128 v[194:197], v170 offset:4096
	s_waitcnt lgkmcnt(7)
	v_mfma_f32_32x32x16_bf16 v[64:79], v[198:201], v[214:217], v[64:79]
	s_waitcnt lgkmcnt(6)
	v_mfma_f32_32x32x16_bf16 v[112:127], v[198:201], v[218:221], v[112:127]
	v_mfma_f32_32x32x16_bf16 v[32:47], v[202:205], v[214:217], v[32:47]
	v_mfma_f32_32x32x16_bf16 v[96:111], v[202:205], v[218:221], v[96:111]
	v_mfma_f32_32x32x16_bf16 v[16:31], v[206:209], v[214:217], v[16:31]
	v_mfma_f32_32x32x16_bf16 v[80:95], v[206:209], v[218:221], v[80:95]
	v_mfma_f32_32x32x16_bf16 v[0:15], v[210:213], v[214:217], v[0:15]
	v_mfma_f32_32x32x16_bf16 v[48:63], v[210:213], v[218:221], v[48:63]
	ds_read_b128 v[198:201], v171
	ds_read_b128 v[202:205], v171 offset:4096
	ds_read_b128 v[206:209], v171 offset:8192
	ds_read_b128 v[210:213], v171 offset:12288
	ds_read_b128 v[214:217], v172
	ds_read_b128 v[218:221], v172 offset:4096
	s_waitcnt lgkmcnt(7)
	v_mfma_f32_32x32x16_bf16 v[64:79], v[158:161], v[190:193], v[64:79]
	s_waitcnt lgkmcnt(6)
	v_mfma_f32_32x32x16_bf16 v[112:127], v[158:161], v[194:197], v[112:127]
	v_mfma_f32_32x32x16_bf16 v[32:47], v[178:181], v[190:193], v[32:47]
	v_mfma_f32_32x32x16_bf16 v[96:111], v[178:181], v[194:197], v[96:111]
	v_mfma_f32_32x32x16_bf16 v[16:31], v[182:185], v[190:193], v[16:31]
	v_mfma_f32_32x32x16_bf16 v[80:95], v[182:185], v[194:197], v[80:95]
	v_mfma_f32_32x32x16_bf16 v[0:15], v[186:189], v[190:193], v[0:15]
	v_mfma_f32_32x32x16_bf16 v[48:63], v[186:189], v[194:197], v[48:63]
	s_waitcnt lgkmcnt(1)
	v_mfma_f32_32x32x16_bf16 v[64:79], v[198:201], v[214:217], v[64:79]
	s_waitcnt lgkmcnt(0)
	v_mfma_f32_32x32x16_bf16 v[112:127], v[198:201], v[218:221], v[112:127]
	v_mfma_f32_32x32x16_bf16 v[32:47], v[202:205], v[214:217], v[32:47]
	v_mfma_f32_32x32x16_bf16 v[96:111], v[202:205], v[218:221], v[96:111]
	v_mfma_f32_32x32x16_bf16 v[16:31], v[206:209], v[214:217], v[16:31]
	v_mfma_f32_32x32x16_bf16 v[80:95], v[206:209], v[218:221], v[80:95]
	v_mfma_f32_32x32x16_bf16 v[0:15], v[210:213], v[214:217], v[0:15]
	v_mfma_f32_32x32x16_bf16 v[48:63], v[210:213], v[218:221], v[48:63]
	v_mov_b32_e32 v128, v139
	v_mov_b32_e32 v161, v137
	v_mov_b32_e32 v177, v135
	s_barrier
	s_nop 0
	v_lshl_add_u32 v160, s11, 8, v145
	s_ashr_i32 s11, s10, 31
	s_lshl_b64 s[10:11], s[10:11], 8
	v_mov_b32_e32 v159, s11
	v_or_b32_e32 v158, s10, v134
	v_cmp_gt_i32_e32 vcc, s14, v160
	s_and_saveexec_b64 s[10:11], vcc
	s_xor_b64 s[10:11], exec, s[10:11]
	s_cbranch_execz .LBB0_132
	v_lshlrev_b32_e32 v149, 1, v161
	v_mul_lo_u32 v128, v128, s15
	v_add3_u32 v128, v163, v149, v128
	v_cvt_pk_bf16_f32 v0, v0, s0
	v_cvt_pk_bf16_f32 v64, v64, s0
	v_cvt_pk_bf16_f32 v32, v32, s0
	v_cvt_pk_bf16_f32 v16, v16, s0
	ds_write_b16 v128, v0 offset:13824
	v_cvt_pk_bf16_f32 v0, v1, s0
	ds_write_b16 v128, v64
	v_cvt_pk_bf16_f32 v64, v65, s0
	ds_write_b16 v128, v32 offset:4608
	v_cvt_pk_bf16_f32 v32, v33, s0
	ds_write_b16 v128, v16 offset:9216
	v_cvt_pk_bf16_f32 v16, v17, s0
	ds_write_b16 v128, v0 offset:13968
	v_cvt_pk_bf16_f32 v0, v2, s0
	ds_write_b16 v128, v64 offset:144
	v_cvt_pk_bf16_f32 v64, v66, s0
	ds_write_b16 v128, v32 offset:4752
	v_cvt_pk_bf16_f32 v32, v34, s0
	ds_write_b16 v128, v16 offset:9360
	v_cvt_pk_bf16_f32 v16, v18, s0
	ds_write_b16 v128, v0 offset:14112
	v_cvt_pk_bf16_f32 v0, v3, s0
	ds_write_b16 v128, v64 offset:288
	v_cvt_pk_bf16_f32 v64, v67, s0
	ds_write_b16 v128, v32 offset:4896
	v_cvt_pk_bf16_f32 v32, v35, s0
	ds_write_b16 v128, v16 offset:9504
	v_cvt_pk_bf16_f32 v16, v19, s0
	ds_write_b16 v128, v0 offset:14256
	v_cvt_pk_bf16_f32 v0, v4, s0
	ds_write_b16 v128, v64 offset:432
	v_cvt_pk_bf16_f32 v64, v68, s0
	ds_write_b16 v128, v32 offset:5040
	v_cvt_pk_bf16_f32 v32, v36, s0
	ds_write_b16 v128, v16 offset:9648
	v_cvt_pk_bf16_f32 v16, v20, s0
	ds_write_b16 v128, v0 offset:14976
	v_cvt_pk_bf16_f32 v0, v5, s0
	ds_write_b16 v128, v64 offset:1152
	v_cvt_pk_bf16_f32 v64, v69, s0
	ds_write_b16 v128, v32 offset:5760
	v_cvt_pk_bf16_f32 v32, v37, s0
	ds_write_b16 v128, v16 offset:10368
	v_cvt_pk_bf16_f32 v16, v21, s0
	ds_write_b16 v128, v0 offset:15120
	v_cvt_pk_bf16_f32 v0, v6, s0
	ds_write_b16 v128, v64 offset:1296
	v_cvt_pk_bf16_f32 v64, v70, s0
	ds_write_b16 v128, v32 offset:5904
	v_cvt_pk_bf16_f32 v32, v38, s0
	ds_write_b16 v128, v16 offset:10512
	v_cvt_pk_bf16_f32 v16, v22, s0
	ds_write_b16 v128, v0 offset:15264
	v_cvt_pk_bf16_f32 v0, v7, s0
	ds_write_b16 v128, v64 offset:1440
; __device__ __forceinline__ int accrow(int reg, int lh) { return (reg & 3) + 8 * (reg >> 2) + 4 * lh; }
; template <int EPI, int PN>
; __device__ void gemm_phase(const Params& p, const u16* __restrict__ A, const u16* __restrict__ Bt, int nNt, char* smem) {
;     ...
; #pragma unroll
;       for (int i = 0; i < 4; ++i)
; #pragma unroll
;         for (int j = 0; j < 2; ++j)
; #pragma unroll
;           for (int r = 0; r < 16; ++r) *(u16*)(et + (i * 32 + accrow(r, lhE)) * 144 + (j * 32 + lrE) * 2) = f2bf(acc[i][j][r]);
	v_cvt_pk_bf16_f32 v64, v71, s0
	ds_write_b16 v128, v32 offset:6048
	v_cvt_pk_bf16_f32 v32, v39, s0
	ds_write_b16 v128, v16 offset:10656
	v_cvt_pk_bf16_f32 v16, v23, s0
	ds_write_b16 v128, v0 offset:15408
	v_cvt_pk_bf16_f32 v0, v8, s0
	ds_write_b16 v128, v64 offset:1584
	v_cvt_pk_bf16_f32 v64, v72, s0
	ds_write_b16 v128, v32 offset:6192
	v_cvt_pk_bf16_f32 v32, v40, s0
	ds_write_b16 v128, v16 offset:10800
	v_cvt_pk_bf16_f32 v16, v24, s0
	ds_write_b16 v128, v0 offset:16128
	v_cvt_pk_bf16_f32 v0, v9, s0
	ds_write_b16 v128, v64 offset:2304
	v_cvt_pk_bf16_f32 v64, v73, s0
	ds_write_b16 v128, v32 offset:6912
	v_cvt_pk_bf16_f32 v32, v41, s0
	ds_write_b16 v128, v16 offset:11520
	v_cvt_pk_bf16_f32 v16, v25, s0
	ds_write_b16 v128, v0 offset:16272
	v_cvt_pk_bf16_f32 v0, v10, s0
	ds_write_b16 v128, v64 offset:2448
	v_cvt_pk_bf16_f32 v64, v74, s0
	ds_write_b16 v128, v32 offset:7056
	v_cvt_pk_bf16_f32 v32, v42, s0
	ds_write_b16 v128, v16 offset:11664
	v_cvt_pk_bf16_f32 v16, v26, s0
	ds_write_b16 v128, v0 offset:16416
	v_cvt_pk_bf16_f32 v0, v11, s0
	ds_write_b16 v128, v64 offset:2592
	v_cvt_pk_bf16_f32 v64, v75, s0
	ds_write_b16 v128, v32 offset:7200
	v_cvt_pk_bf16_f32 v32, v43, s0
	ds_write_b16 v128, v16 offset:11808
	v_cvt_pk_bf16_f32 v16, v27, s0
	ds_write_b16 v128, v0 offset:16560
	v_cvt_pk_bf16_f32 v0, v12, s0
	ds_write_b16 v128, v64 offset:2736
	v_cvt_pk_bf16_f32 v64, v76, s0
	ds_write_b16 v128, v32 offset:7344
	v_cvt_pk_bf16_f32 v32, v44, s0
	ds_write_b16 v128, v16 offset:11952
	v_cvt_pk_bf16_f32 v16, v28, s0
	ds_write_b16 v128, v0 offset:17280
	v_cvt_pk_bf16_f32 v0, v13, s0
	ds_write_b16 v128, v64 offset:3456
	v_cvt_pk_bf16_f32 v64, v77, s0
	ds_write_b16 v128, v32 offset:8064
	v_cvt_pk_bf16_f32 v32, v45, s0
	ds_write_b16 v128, v16 offset:12672
	v_cvt_pk_bf16_f32 v16, v29, s0
	ds_write_b16 v128, v0 offset:17424
	v_cvt_pk_bf16_f32 v0, v14, s0
	ds_write_b16 v128, v64 offset:3600
	v_cvt_pk_bf16_f32 v64, v78, s0
	ds_write_b16 v128, v32 offset:8208
	v_cvt_pk_bf16_f32 v32, v46, s0
	ds_write_b16 v128, v16 offset:12816
	v_cvt_pk_bf16_f32 v16, v30, s0
	ds_write_b16 v128, v0 offset:17568
	v_cvt_pk_bf16_f32 v0, v15, s0
	ds_write_b16 v128, v64 offset:3744
	v_cvt_pk_bf16_f32 v64, v79, s0
	ds_write_b16 v128, v32 offset:8352
	v_cvt_pk_bf16_f32 v32, v47, s0
	ds_write_b16 v128, v16 offset:12960
	v_cvt_pk_bf16_f32 v16, v31, s0
	ds_write_b16 v128, v0 offset:17712
	v_cvt_pk_bf16_f32 v0, v48, s0
	ds_write_b16 v128, v64 offset:3888
	v_cvt_pk_bf16_f32 v64, v112, s0
	ds_write_b16 v128, v32 offset:8496
	v_cvt_pk_bf16_f32 v32, v96, s0
	ds_write_b16 v128, v16 offset:13104
	v_cvt_pk_bf16_f32 v16, v80, s0
	ds_write_b16 v128, v0 offset:13888
	v_cvt_pk_bf16_f32 v0, v49, s0
	ds_write_b16 v128, v64 offset:64
	v_cvt_pk_bf16_f32 v64, v113, s0
	ds_write_b16 v128, v32 offset:4672
	v_cvt_pk_bf16_f32 v32, v97, s0
	ds_write_b16 v128, v16 offset:9280
	v_cvt_pk_bf16_f32 v16, v81, s0
	ds_write_b16 v128, v0 offset:14032
	v_cvt_pk_bf16_f32 v0, v50, s0
	ds_write_b16 v128, v64 offset:208
	v_cvt_pk_bf16_f32 v64, v114, s0
	ds_write_b16 v128, v32 offset:4816
	v_cvt_pk_bf16_f32 v32, v98, s0
	ds_write_b16 v128, v16 offset:9424
	v_cvt_pk_bf16_f32 v16, v82, s0
	ds_write_b16 v128, v0 offset:14176
	v_cvt_pk_bf16_f32 v0, v51, s0
	ds_write_b16 v128, v64 offset:352
	v_cvt_pk_bf16_f32 v64, v115, s0
	ds_write_b16 v128, v32 offset:4960
	v_cvt_pk_bf16_f32 v32, v99, s0
	ds_write_b16 v128, v16 offset:9568
	v_cvt_pk_bf16_f32 v16, v83, s0
	ds_write_b16 v128, v0 offset:14320
	v_cvt_pk_bf16_f32 v0, v52, s0
	ds_write_b16 v128, v64 offset:496
	v_cvt_pk_bf16_f32 v64, v116, s0
	ds_write_b16 v128, v32 offset:5104
	v_cvt_pk_bf16_f32 v32, v100, s0
	ds_write_b16 v128, v16 offset:9712
	v_cvt_pk_bf16_f32 v16, v84, s0
	ds_write_b16 v128, v0 offset:15040
	v_cvt_pk_bf16_f32 v0, v53, s0
	ds_write_b16 v128, v64 offset:1216
	v_cvt_pk_bf16_f32 v64, v117, s0
	ds_write_b16 v128, v32 offset:5824
	v_cvt_pk_bf16_f32 v32, v101, s0
	ds_write_b16 v128, v16 offset:10432
	v_cvt_pk_bf16_f32 v16, v85, s0
	ds_write_b16 v128, v0 offset:15184
	v_cvt_pk_bf16_f32 v0, v54, s0
	ds_write_b16 v128, v64 offset:1360
	v_cvt_pk_bf16_f32 v64, v118, s0
	ds_write_b16 v128, v32 offset:5968
	v_cvt_pk_bf16_f32 v32, v102, s0
	ds_write_b16 v128, v16 offset:10576
	v_cvt_pk_bf16_f32 v16, v86, s0
	ds_write_b16 v128, v0 offset:15328
	v_cvt_pk_bf16_f32 v0, v55, s0
	ds_write_b16 v128, v64 offset:1504
	v_cvt_pk_bf16_f32 v64, v119, s0
	ds_write_b16 v128, v32 offset:6112
	v_cvt_pk_bf16_f32 v32, v103, s0
	ds_write_b16 v128, v16 offset:10720
	v_cvt_pk_bf16_f32 v16, v87, s0
	ds_write_b16 v128, v0 offset:15472
	v_cvt_pk_bf16_f32 v0, v56, s0
	ds_write_b16 v128, v64 offset:1648
	v_cvt_pk_bf16_f32 v64, v120, s0
	ds_write_b16 v128, v32 offset:6256
	v_cvt_pk_bf16_f32 v32, v104, s0
	ds_write_b16 v128, v16 offset:10864
	v_cvt_pk_bf16_f32 v16, v88, s0
	ds_write_b16 v128, v0 offset:16192
	v_cvt_pk_bf16_f32 v0, v57, s0
	ds_write_b16 v128, v64 offset:2368
	v_cvt_pk_bf16_f32 v64, v121, s0
	ds_write_b16 v128, v32 offset:6976
	v_cvt_pk_bf16_f32 v32, v105, s0
	ds_write_b16 v128, v16 offset:11584
	v_cvt_pk_bf16_f32 v16, v89, s0
	ds_write_b16 v128, v0 offset:16336
	v_cvt_pk_bf16_f32 v0, v58, s0
	ds_write_b16 v128, v64 offset:2512
	v_cvt_pk_bf16_f32 v64, v122, s0
	ds_write_b16 v128, v32 offset:7120
	v_cvt_pk_bf16_f32 v32, v106, s0
	ds_write_b16 v128, v16 offset:11728
	v_cvt_pk_bf16_f32 v16, v90, s0
	ds_write_b16 v128, v0 offset:16480
	v_cvt_pk_bf16_f32 v0, v59, s0
	ds_write_b16 v128, v64 offset:2656
	v_cvt_pk_bf16_f32 v64, v123, s0
	ds_write_b16 v128, v32 offset:7264
	v_cvt_pk_bf16_f32 v32, v107, s0
	ds_write_b16 v128, v16 offset:11872
	v_cvt_pk_bf16_f32 v16, v91, s0
	ds_write_b16 v128, v0 offset:16624
; __device__ __forceinline__ int accrow(int reg, int lh) { return (reg & 3) + 8 * (reg >> 2) + 4 * lh; }
; template <int EPI, int PN>
; __device__ void gemm_phase(const Params& p, const u16* __restrict__ A, const u16* __restrict__ Bt, int nNt, char* smem) {
;     ...
;           for (int r = 0; r < 16; ++r) *(u16*)(et + (i * 32 + accrow(r, lhE)) * 144 + (j * 32 + lrE) * 2) = f2bf(acc[i][j][r]);
; #pragma unroll
;       for (int it = 0; it < 16; ++it) {
;         const int c = it * 64 + laneE, row = c >> 3, seg = c & 7;
;         const uint4 v = *(const uint4*)(et + row * 144 + seg * 16);
;         if (EPI == 0) *(uint4*)(p.proj + (row0 + row) * NPROJ + col0 + seg * 8) = v;
;         else *(uint4*)(p.qp + (row0 + row) * DM + col0 + seg * 8) = v;
	v_cvt_pk_bf16_f32 v0, v60, s0
	ds_write_b16 v128, v64 offset:2800
	v_cvt_pk_bf16_f32 v64, v124, s0
	ds_write_b16 v128, v32 offset:7408
	v_cvt_pk_bf16_f32 v32, v108, s0
	ds_write_b16 v128, v16 offset:12016
	v_cvt_pk_bf16_f32 v16, v92, s0
	ds_write_b16 v128, v0 offset:17344
	v_cvt_pk_bf16_f32 v0, v61, s0
	ds_write_b16 v128, v64 offset:3520
	v_cvt_pk_bf16_f32 v64, v125, s0
	ds_write_b16 v128, v32 offset:8128
	v_cvt_pk_bf16_f32 v32, v109, s0
	ds_write_b16 v128, v16 offset:12736
	v_cvt_pk_bf16_f32 v16, v93, s0
	ds_write_b16 v128, v0 offset:17488
	v_cvt_pk_bf16_f32 v0, v62, s0
	ds_write_b16 v128, v64 offset:3664
	v_cvt_pk_bf16_f32 v64, v126, s0
	ds_write_b16 v128, v32 offset:8272
	v_cvt_pk_bf16_f32 v32, v110, s0
	ds_write_b16 v128, v16 offset:12880
	v_cvt_pk_bf16_f32 v16, v94, s0
	ds_write_b16 v128, v0 offset:17632
	v_cvt_pk_bf16_f32 v0, v63, s0
	ds_write_b16 v128, v64 offset:3808
	v_cvt_pk_bf16_f32 v64, v127, s0
	ds_write_b16 v128, v32 offset:8416
	v_cvt_pk_bf16_f32 v32, v111, s0
	ds_write_b16 v128, v16 offset:13024
	v_cvt_pk_bf16_f32 v16, v95, s0
	ds_write_b16 v128, v0 offset:17776
	v_lshlrev_b32_e32 v0, 4, v177
	ds_write_b16 v128, v64 offset:3952
	ds_write_b16 v128, v32 offset:8560
	ds_write_b16 v128, v16 offset:13168
	v_and_b32_e32 v128, 0x70, v0
	v_add_u32_e32 v0, v163, v128
	v_ashrrev_i32_e32 v6, 3, v177
	v_readlane_b32 s36, v253, 39
	v_mad_u64_u32 v[2:3], s[12:13], v6, s16, v[0:1]
	v_ashrrev_i32_e32 v7, 31, v6
	v_readlane_b32 s40, v253, 43
	v_readlane_b32 s41, v253, 44
	ds_read_b128 v[2:5], v2
	v_lshl_add_u64 v[6:7], v[158:159], 0, v[6:7]
	v_mov_b64_e32 v[10:11], s[40:41]
	v_ashrrev_i32_e32 v161, 31, v160
	v_mad_u64_u32 v[8:9], s[12:13], v6, s17, v[10:11]
	v_mad_i32_i24 v9, v7, s17, v9
	v_lshlrev_b64 v[12:13], 1, v[160:161]
	v_add_u32_e32 v1, 64, v177
	v_lshl_add_u64 v[6:7], v[8:9], 0, v[12:13]
	v_ashrrev_i32_e32 v16, 3, v1
	v_lshl_add_u64 v[14:15], v[6:7], 0, v[128:129]
	v_mad_u64_u32 v[6:7], s[12:13], v16, s16, v[0:1]
	v_ashrrev_i32_e32 v17, 31, v16
	ds_read_b128 v[6:9], v6
	s_waitcnt lgkmcnt(1)
	global_store_dwordx4 v[14:15], v[2:5], off
	v_add_u32_e32 v1, 0x80, v177
	v_readlane_b32 s37, v253, 40
	v_lshl_add_u64 v[2:3], v[158:159], 0, v[16:17]
	v_mad_u64_u32 v[4:5], s[12:13], v2, s17, v[10:11]
	v_mad_i32_i24 v5, v3, s17, v5
	v_lshl_add_u64 v[2:3], v[4:5], 0, v[12:13]
	v_lshl_add_u64 v[2:3], v[2:3], 0, v[128:129]
	s_waitcnt lgkmcnt(0)
	global_store_dwordx4 v[2:3], v[6:9], off
	v_readlane_b32 s38, v253, 41
	v_readlane_b32 s39, v253, 42
	v_ashrrev_i32_e32 v6, 3, v1
	v_mad_u64_u32 v[2:3], s[12:13], v6, s16, v[0:1]
	v_ashrrev_i32_e32 v7, 31, v6
	ds_read_b128 v[2:5], v2
	v_lshl_add_u64 v[6:7], v[158:159], 0, v[6:7]
	v_mad_u64_u32 v[8:9], s[12:13], v6, s17, v[10:11]
	v_mad_i32_i24 v9, v7, s17, v9
	v_add_u32_e32 v1, 0xc0, v177
	v_lshl_add_u64 v[6:7], v[8:9], 0, v[12:13]
	v_ashrrev_i32_e32 v16, 3, v1
	v_lshl_add_u64 v[14:15], v[6:7], 0, v[128:129]
	v_mad_u64_u32 v[6:7], s[12:13], v16, s16, v[0:1]
	v_ashrrev_i32_e32 v17, 31, v16
	ds_read_b128 v[6:9], v6
	s_waitcnt lgkmcnt(1)
	global_store_dwordx4 v[14:15], v[2:5], off
	v_add_u32_e32 v1, 0x100, v177
	v_readlane_b32 s42, v253, 45
	v_lshl_add_u64 v[2:3], v[158:159], 0, v[16:17]
	v_mad_u64_u32 v[4:5], s[12:13], v2, s17, v[10:11]
	v_mad_i32_i24 v5, v3, s17, v5
	v_lshl_add_u64 v[2:3], v[4:5], 0, v[12:13]
	v_lshl_add_u64 v[2:3], v[2:3], 0, v[128:129]
	s_waitcnt lgkmcnt(0)
	global_store_dwordx4 v[2:3], v[6:9], off
	v_readlane_b32 s43, v253, 46
	v_readlane_b32 s44, v253, 47
	v_ashrrev_i32_e32 v6, 3, v1
	v_mad_u64_u32 v[2:3], s[12:13], v6, s16, v[0:1]
	v_ashrrev_i32_e32 v7, 31, v6
	ds_read_b128 v[2:5], v2
	v_lshl_add_u64 v[6:7], v[158:159], 0, v[6:7]
	v_mad_u64_u32 v[8:9], s[12:13], v6, s17, v[10:11]
	v_mad_i32_i24 v9, v7, s17, v9
	v_add_u32_e32 v1, 0x140, v177
	v_lshl_add_u64 v[6:7], v[8:9], 0, v[12:13]
	v_ashrrev_i32_e32 v16, 3, v1
	v_lshl_add_u64 v[14:15], v[6:7], 0, v[128:129]
	v_mad_u64_u32 v[6:7], s[12:13], v16, s16, v[0:1]
	v_ashrrev_i32_e32 v17, 31, v16
	ds_read_b128 v[6:9], v6
	s_waitcnt lgkmcnt(1)
	global_store_dwordx4 v[14:15], v[2:5], off
	v_add_u32_e32 v1, 0x180, v177
	v_readlane_b32 s45, v253, 48
	v_lshl_add_u64 v[2:3], v[158:159], 0, v[16:17]
	v_mad_u64_u32 v[4:5], s[12:13], v2, s17, v[10:11]
	v_mad_i32_i24 v5, v3, s17, v5
	v_lshl_add_u64 v[2:3], v[4:5], 0, v[12:13]
	v_lshl_add_u64 v[2:3], v[2:3], 0, v[128:129]
	s_waitcnt lgkmcnt(0)
; template <int EPI, int PN>
; __device__ void gemm_phase(const Params& p, const u16* __restrict__ A, const u16* __restrict__ Bt, int nNt, char* smem) {
;     ...
;       for (int it = 0; it < 16; ++it) {
;         const int c = it * 64 + laneE, row = c >> 3, seg = c & 7;
;         const uint4 v = *(const uint4*)(et + row * 144 + seg * 16);
;         if (EPI == 0) *(uint4*)(p.proj + (row0 + row) * NPROJ + col0 + seg * 8) = v;
;         else *(uint4*)(p.qp + (row0 + row) * DM + col0 + seg * 8) = v;
;       }
	global_store_dwordx4 v[2:3], v[6:9], off
	v_readlane_b32 s46, v253, 49
	v_readlane_b32 s47, v253, 50
	v_ashrrev_i32_e32 v6, 3, v1
	v_mad_u64_u32 v[2:3], s[12:13], v6, s16, v[0:1]
	v_ashrrev_i32_e32 v7, 31, v6
	ds_read_b128 v[2:5], v2
	v_lshl_add_u64 v[6:7], v[158:159], 0, v[6:7]
	v_mad_u64_u32 v[8:9], s[12:13], v6, s17, v[10:11]
	v_mad_i32_i24 v9, v7, s17, v9
	v_add_u32_e32 v1, 0x1c0, v177
	v_lshl_add_u64 v[6:7], v[8:9], 0, v[12:13]
	v_ashrrev_i32_e32 v16, 3, v1
	v_lshl_add_u64 v[14:15], v[6:7], 0, v[128:129]
	v_mad_u64_u32 v[6:7], s[12:13], v16, s16, v[0:1]
	v_ashrrev_i32_e32 v17, 31, v16
	ds_read_b128 v[6:9], v6
	s_waitcnt lgkmcnt(1)
	global_store_dwordx4 v[14:15], v[2:5], off
	v_add_u32_e32 v1, 0x200, v177
	v_readlane_b32 s48, v253, 51
	v_lshl_add_u64 v[2:3], v[158:159], 0, v[16:17]
	v_mad_u64_u32 v[4:5], s[12:13], v2, s17, v[10:11]
	v_mad_i32_i24 v5, v3, s17, v5
	v_lshl_add_u64 v[2:3], v[4:5], 0, v[12:13]
	v_lshl_add_u64 v[2:3], v[2:3], 0, v[128:129]
	s_waitcnt lgkmcnt(0)
	global_store_dwordx4 v[2:3], v[6:9], off
	v_readlane_b32 s49, v253, 52
	v_readlane_b32 s50, v253, 53
	v_ashrrev_i32_e32 v6, 3, v1
	v_mad_u64_u32 v[2:3], s[12:13], v6, s16, v[0:1]
	v_ashrrev_i32_e32 v7, 31, v6
	ds_read_b128 v[2:5], v2
	v_lshl_add_u64 v[6:7], v[158:159], 0, v[6:7]
	v_mad_u64_u32 v[8:9], s[12:13], v6, s17, v[10:11]
	v_mad_i32_i24 v9, v7, s17, v9
	v_add_u32_e32 v1, 0x240, v177
	v_lshl_add_u64 v[6:7], v[8:9], 0, v[12:13]
	v_ashrrev_i32_e32 v16, 3, v1
	v_lshl_add_u64 v[14:15], v[6:7], 0, v[128:129]
	v_mad_u64_u32 v[6:7], s[12:13], v16, s16, v[0:1]
	v_ashrrev_i32_e32 v17, 31, v16
	ds_read_b128 v[6:9], v6
	s_waitcnt lgkmcnt(1)
	global_store_dwordx4 v[14:15], v[2:5], off
	v_add_u32_e32 v1, 0x280, v177
	v_readlane_b32 s51, v253, 54
	v_lshl_add_u64 v[2:3], v[158:159], 0, v[16:17]
	v_mad_u64_u32 v[4:5], s[12:13], v2, s17, v[10:11]
	v_mad_i32_i24 v5, v3, s17, v5
	v_lshl_add_u64 v[2:3], v[4:5], 0, v[12:13]
	v_lshl_add_u64 v[2:3], v[2:3], 0, v[128:129]
	s_waitcnt lgkmcnt(0)
	global_store_dwordx4 v[2:3], v[6:9], off
	s_nop 1
	v_ashrrev_i32_e32 v6, 3, v1
	v_mad_u64_u32 v[2:3], s[12:13], v6, s16, v[0:1]
	v_ashrrev_i32_e32 v7, 31, v6
	ds_read_b128 v[2:5], v2
	v_lshl_add_u64 v[6:7], v[158:159], 0, v[6:7]
	v_mad_u64_u32 v[8:9], s[12:13], v6, s17, v[10:11]
	v_mad_i32_i24 v9, v7, s17, v9
	v_add_u32_e32 v1, 0x2c0, v177
	v_lshl_add_u64 v[6:7], v[8:9], 0, v[12:13]
	v_ashrrev_i32_e32 v16, 3, v1
	v_lshl_add_u64 v[14:15], v[6:7], 0, v[128:129]
	v_mad_u64_u32 v[6:7], s[12:13], v16, s16, v[0:1]
	v_ashrrev_i32_e32 v17, 31, v16
	ds_read_b128 v[6:9], v6
	s_waitcnt lgkmcnt(1)
	global_store_dwordx4 v[14:15], v[2:5], off
	v_add_u32_e32 v1, 0x300, v177
	s_nop 0
	v_lshl_add_u64 v[2:3], v[158:159], 0, v[16:17]
	v_mad_u64_u32 v[4:5], s[12:13], v2, s17, v[10:11]
	v_mad_i32_i24 v5, v3, s17, v5
	v_lshl_add_u64 v[2:3], v[4:5], 0, v[12:13]
	v_lshl_add_u64 v[2:3], v[2:3], 0, v[128:129]
	s_waitcnt lgkmcnt(0)
	global_store_dwordx4 v[2:3], v[6:9], off
	s_nop 1
	v_ashrrev_i32_e32 v6, 3, v1
	v_mad_u64_u32 v[2:3], s[12:13], v6, s16, v[0:1]
	v_ashrrev_i32_e32 v7, 31, v6
	ds_read_b128 v[2:5], v2
	v_lshl_add_u64 v[6:7], v[158:159], 0, v[6:7]
	v_mad_u64_u32 v[8:9], s[12:13], v6, s17, v[10:11]
	v_mad_i32_i24 v9, v7, s17, v9
	v_add_u32_e32 v1, 0x340, v177
	v_lshl_add_u64 v[6:7], v[8:9], 0, v[12:13]
	v_ashrrev_i32_e32 v16, 3, v1
	v_lshl_add_u64 v[14:15], v[6:7], 0, v[128:129]
	v_mad_u64_u32 v[6:7], s[12:13], v16, s16, v[0:1]
	v_ashrrev_i32_e32 v17, 31, v16
	ds_read_b128 v[6:9], v6
	s_waitcnt lgkmcnt(1)
	global_store_dwordx4 v[14:15], v[2:5], off
	v_add_u32_e32 v1, 0x380, v177
	s_nop 0
	v_lshl_add_u64 v[2:3], v[158:159], 0, v[16:17]
	v_mad_u64_u32 v[4:5], s[12:13], v2, s17, v[10:11]
	v_mad_i32_i24 v5, v3, s17, v5
	v_lshl_add_u64 v[2:3], v[4:5], 0, v[12:13]
	v_lshl_add_u64 v[2:3], v[2:3], 0, v[128:129]
	s_waitcnt lgkmcnt(0)
	global_store_dwordx4 v[2:3], v[6:9], off
	s_nop 1
	v_ashrrev_i32_e32 v6, 3, v1
	v_mad_u64_u32 v[2:3], s[12:13], v6, s16, v[0:1]
	v_ashrrev_i32_e32 v7, 31, v6
	ds_read_b128 v[2:5], v2
	v_lshl_add_u64 v[6:7], v[158:159], 0, v[6:7]
	v_mad_u64_u32 v[8:9], s[12:13], v6, s17, v[10:11]
	v_add_u32_e32 v1, 0x3c0, v177
	v_mad_i32_i24 v9, v7, s17, v9
	v_ashrrev_i32_e32 v16, 3, v1
	v_lshl_add_u64 v[6:7], v[8:9], 0, v[12:13]
	v_mad_u64_u32 v[0:1], s[12:13], v16, s16, v[0:1]
	v_ashrrev_i32_e32 v17, 31, v16
	v_lshl_add_u64 v[14:15], v[6:7], 0, v[128:129]
	ds_read_b128 v[6:9], v0
	v_lshl_add_u64 v[0:1], v[158:159], 0, v[16:17]
	s_waitcnt lgkmcnt(1)
	global_store_dwordx4 v[14:15], v[2:5], off
	s_nop 1
	v_mad_u64_u32 v[2:3], s[12:13], v0, s17, v[10:11]
	v_mad_i32_i24 v3, v1, s17, v3
	v_lshl_add_u64 v[0:1], v[2:3], 0, v[12:13]
	v_lshl_add_u64 v[0:1], v[0:1], 0, v[128:129]
	s_waitcnt lgkmcnt(0)
	global_store_dwordx4 v[0:1], v[6:9], off

; template <int EPI, int PN>
; __device__ void gemm_phase(const Params& p, const u16* __restrict__ A, const u16* __restrict__ Bt, int nNt, char* smem) {
;     ...
;     for (int kt = 0; kt < 32; ++kt) {
;       asm volatile("s_waitcnt vmcnt(0)" ::: "memory");
;       __builtin_amdgcn_s_barrier();
;       const u16* Ab = ring + (kt & 1) * STG;
;       const u16* Bb = Ab + 16384;
;       u16* st = ring + ((kt + 1) & 1) * STG;
;       const bool pre = (kt + 1 < 32);
;       s16x8 af[2][4], bf[2][2];
;       auto ldfrag = [&](int ks, int slot) {
; #pragma unroll
;         for (int i = 0; i < 4; ++i) {
;           const int row = wr * 128 + i * 32 + lr;
;           af[slot][i] = *(const s16x8*)(Ab + row * 64 + (((ks * 2 + lh) ^ ((row >> 1) & 7)) * 8));
;         }
; #pragma unroll
;         for (int j = 0; j < 2; ++j) {
;           const int rowb = nh * 128 + wc * 64 + j * 32 + lr;
;           bf[slot][j] = *(const s16x8*)(Bb + rowb * 64 + (((ks * 2 + lh) ^ ((rowb >> 1) & 7)) * 8));
;         }
;       };
;       ldfrag(0, 0);
;       ldfrag(1, 1);
;       __builtin_amdgcn_sched_barrier(0);
; #pragma unroll
;       for (int ks = 0; ks < 4; ++ks) {
;         const int slot = ks & 1;
; #pragma unroll
;         for (int i = 0; i < 4; ++i) {
;           acc[i][0] = mfma32(af[slot][i], bf[slot][0], acc[i][0]);
;           acc[i][1] = mfma32(af[slot][i], bf[slot][1], acc[i][1]);
;           __builtin_amdgcn_sched_barrier(0);
;           if (pre && (i & 1) == 0) {
;             const int pi = ks * 2 + (i >> 1);
;             if (pi < 4) glds16(Ag0 + (size_t)pi * 64 * LDK + (kt + 1) * 64, st + (srow + 64 * pi) * 64 + sch * 8);
;             else glds16(Bg0 + (size_t)(pi - 4) * 64 * LDK + (kt + 1) * 64, st + 16384 + (srow + 64 * (pi - 4)) * 64 + sch * 8);
;             __builtin_amdgcn_sched_barrier(0);
;           }
;         }
;         if (ks + 2 < 4) { ldfrag(ks + 2, slot); __builtin_amdgcn_sched_barrier(0); }
;       }
.Lrot723_loop:
	s_add_i32 s15, s11, 0xffff8000
	s_and_b32 s15, s15, 0x8000
	s_lshl_b32 s15, s15, 1
	v_lshl_or_b32 v128, v143, 1, s15
	v_lshl_add_u32 v149, v147, 1, s15
	s_and_b32 s98, s11, 0x8000
	s_lshl_b32 s98, s98, 1
	s_waitcnt lgkmcnt(7)
	v_mfma_f32_32x32x16_bf16 v[112:127], v[178:181], v[194:197], v[112:127]
	v_add3_u32 v226, s98, v162, v156
	s_waitcnt lgkmcnt(6)
	v_mfma_f32_32x32x16_bf16 v[96:111], v[178:181], v[198:201], v[96:111]
	v_readfirstlane_b32 s100, v226
	s_mov_b32 s16, m0
	s_add_i32 m0, s100, 0x8000
	s_nop 0
	global_load_lds_dwordx4 v[160:161], off
	v_mfma_f32_32x32x16_bf16 v[80:95], v[182:185], v[194:197], v[80:95]
	v_lshl_add_u64 v[178:179], v[160:161], 0, s[2:3]
	s_add_i32 m0, s100, 0xa000
	s_nop 0
	global_load_lds_dwordx4 v[178:179], off
	v_mfma_f32_32x32x16_bf16 v[64:79], v[182:185], v[198:201], v[64:79]
	v_lshl_add_u64 v[180:181], v[160:161], 0, s[4:5]
	s_add_i32 m0, s100, 0xc000
	s_nop 0
	global_load_lds_dwordx4 v[180:181], off
	v_mfma_f32_32x32x16_bf16 v[48:63], v[186:189], v[194:197], v[48:63]
	v_lshl_add_u64 v[178:179], v[160:161], 0, s[6:7]
	s_add_i32 m0, s100, 0xe000
	s_nop 0
	global_load_lds_dwordx4 v[178:179], off
	s_mov_b32 m0, s16
	v_mfma_f32_32x32x16_bf16 v[32:47], v[186:189], v[198:201], v[32:47]
	v_mfma_f32_32x32x16_bf16 v[16:31], v[190:193], v[194:197], v[16:31]
	v_mfma_f32_32x32x16_bf16 v[0:15], v[190:193], v[198:201], v[0:15]
	v_lshl_add_u64 v[160:161], v[160:161], 0, s[8:9]
	v_add_u32_e32 v177, v128, v175
	ds_read_b128 v[178:181], v177
	ds_read_b128 v[182:185], v177 offset:4096
	ds_read_b128 v[186:189], v177 offset:8192
	ds_read_b128 v[190:193], v177 offset:12288
	v_add_u32_e32 v177, v149, v175
	ds_read_b128 v[194:197], v177 offset:32768
	ds_read_b128 v[198:201], v177 offset:36864
	s_waitcnt lgkmcnt(7)
	v_mfma_f32_32x32x16_bf16 v[112:127], v[202:205], v[218:221], v[112:127]
	s_waitcnt lgkmcnt(6)
	v_mfma_f32_32x32x16_bf16 v[96:111], v[202:205], v[222:225], v[96:111]
	v_mfma_f32_32x32x16_bf16 v[80:95], v[206:209], v[218:221], v[80:95]
	v_mfma_f32_32x32x16_bf16 v[64:79], v[206:209], v[222:225], v[64:79]
	v_mfma_f32_32x32x16_bf16 v[48:63], v[210:213], v[218:221], v[48:63]
	v_mfma_f32_32x32x16_bf16 v[32:47], v[210:213], v[222:225], v[32:47]
	v_mfma_f32_32x32x16_bf16 v[16:31], v[214:217], v[218:221], v[16:31]
	v_mfma_f32_32x32x16_bf16 v[0:15], v[214:217], v[222:225], v[0:15]
	v_add_u32_e32 v128, v128, v176
	ds_read_b128 v[202:205], v128
	ds_read_b128 v[206:209], v128 offset:4096
	ds_read_b128 v[210:213], v128 offset:8192
	ds_read_b128 v[214:217], v128 offset:12288
	v_add_u32_e32 v128, v149, v176
	ds_read_b128 v[218:221], v128 offset:32768
	ds_read_b128 v[222:225], v128 offset:36864
	s_waitcnt lgkmcnt(7)
	v_mfma_f32_32x32x16_bf16 v[112:127], v[178:181], v[194:197], v[112:127]
	s_waitcnt lgkmcnt(6)
	v_mfma_f32_32x32x16_bf16 v[96:111], v[178:181], v[198:201], v[96:111]
	v_mfma_f32_32x32x16_bf16 v[80:95], v[182:185], v[194:197], v[80:95]
	v_mfma_f32_32x32x16_bf16 v[64:79], v[182:185], v[198:201], v[64:79]
	v_mfma_f32_32x32x16_bf16 v[48:63], v[186:189], v[194:197], v[48:63]
	v_mfma_f32_32x32x16_bf16 v[32:47], v[186:189], v[198:201], v[32:47]
	v_mfma_f32_32x32x16_bf16 v[16:31], v[190:193], v[194:197], v[16:31]
	v_mfma_f32_32x32x16_bf16 v[0:15], v[190:193], v[198:201], v[0:15]
	v_lshl_or_b32 v227, v143, 1, s98
	v_lshl_add_u32 v229, v147, 1, s98
	v_add_u32_e32 v228, v227, v173
	v_add_u32_e32 v230, v229, v173
	s_waitcnt vmcnt(0) lgkmcnt(0)
	s_barrier
	ds_read_b128 v[178:181], v228
	ds_read_b128 v[182:185], v228 offset:4096
	ds_read_b128 v[186:189], v228 offset:8192
	ds_read_b128 v[190:193], v228 offset:12288
	ds_read_b128 v[194:197], v230 offset:32768
	ds_read_b128 v[198:201], v230 offset:36864
	v_add3_u32 v226, s15, v162, v156
	v_mfma_f32_32x32x16_bf16 v[112:127], v[202:205], v[218:221], v[112:127]
	v_readfirstlane_b32 s99, v226
	s_mov_b32 s16, m0
	s_mov_b32 m0, s99
	s_nop 0
	global_load_lds_dwordx4 v[158:159], off
	v_mfma_f32_32x32x16_bf16 v[96:111], v[202:205], v[222:225], v[96:111]
	v_lshl_add_u64 v[232:233], v[158:159], 0, s[2:3]
	s_add_i32 m0, s99, 0x2000
	s_nop 0
	global_load_lds_dwordx4 v[232:233], off
	v_mfma_f32_32x32x16_bf16 v[80:95], v[206:209], v[218:221], v[80:95]
	v_lshl_add_u64 v[234:235], v[158:159], 0, s[4:5]
	s_add_i32 m0, s99, 0x4000
	s_nop 0
	global_load_lds_dwordx4 v[234:235], off
	v_mfma_f32_32x32x16_bf16 v[64:79], v[206:209], v[222:225], v[64:79]
	v_lshl_add_u64 v[232:233], v[158:159], 0, s[6:7]
	s_add_i32 m0, s99, 0x6000
	s_nop 0
	global_load_lds_dwordx4 v[232:233], off
	s_mov_b32 m0, s16
	v_mfma_f32_32x32x16_bf16 v[48:63], v[210:213], v[218:221], v[48:63]
	v_mfma_f32_32x32x16_bf16 v[32:47], v[210:213], v[222:225], v[32:47]
	v_mfma_f32_32x32x16_bf16 v[16:31], v[214:217], v[218:221], v[16:31]
	v_mfma_f32_32x32x16_bf16 v[0:15], v[214:217], v[222:225], v[0:15]
	v_add_u32_e32 v228, v227, v174
	v_add_u32_e32 v230, v229, v174
	ds_read_b128 v[202:205], v228
	ds_read_b128 v[206:209], v228 offset:4096
	ds_read_b128 v[210:213], v228 offset:8192
	ds_read_b128 v[214:217], v228 offset:12288
	ds_read_b128 v[218:221], v230 offset:32768
	ds_read_b128 v[222:225], v230 offset:36864
	s_add_i32 s11, s11, 0x8000
	v_lshl_add_u64 v[158:159], v[158:159], 0, s[8:9]
	s_cmp_eq_u32 s11, 0xf8000
	s_cbranch_scc0 .Lrot723_loop
; template <int EPI, int PN>
; __device__ void gemm_phase(const Params& p, const u16* __restrict__ A, const u16* __restrict__ Bt, int nNt, char* smem) {
;     ...
;   for (int q = jb;; q += NJ) {
;     const int pl = q / (4 * PN), w = q % (4 * PN);
;     const int gp = pl * 8 + xcd;
;     if (gp >= npatch) break;
;     const int mt = (gp / npn) * 4 + (w & 3), nt = (gp % npn) * PN + (w >> 2);
;     const int gch = sch ^ ((srow >> 1) & 7);
;     const u16* Ag0 = A + (size_t)(mt * 256 + srow) * LDK + gch * 8;
;     const u16* Bg0 = Bt + (size_t)(nt * 256 + srow) * LDK + gch * 8;
;     ...
;     for (int kt = 0; kt < 32; ++kt) {
;       asm volatile("s_waitcnt vmcnt(0)" ::: "memory");
;       __builtin_amdgcn_s_barrier();
;       const u16* Ab = ring + (kt & 1) * STG;
;       const u16* Bb = Ab + 16384;
;       u16* st = ring + ((kt + 1) & 1) * STG;
;       const bool pre = (kt + 1 < 32);
;       s16x8 af[2][4], bf[2][2];
;       auto ldfrag = [&](int ks, int slot) {
; #pragma unroll
;         for (int i = 0; i < 4; ++i) {
;           const int row = wr * 128 + i * 32 + lr;
;           af[slot][i] = *(const s16x8*)(Ab + row * 64 + (((ks * 2 + lh) ^ ((row >> 1) & 7)) * 8));
;         }
; #pragma unroll
;         for (int j = 0; j < 2; ++j) {
;           const int rowb = nh * 128 + wc * 64 + j * 32 + lr;
;           bf[slot][j] = *(const s16x8*)(Bb + rowb * 64 + (((ks * 2 + lh) ^ ((rowb >> 1) & 7)) * 8));
;         }
;       };
;       ldfrag(0, 0);
;       ldfrag(1, 1);
;       __builtin_amdgcn_sched_barrier(0);
; #pragma unroll
;       for (int ks = 0; ks < 4; ++ks) {
;         const int slot = ks & 1;
; #pragma unroll
;         for (int i = 0; i < 4; ++i) {
;           acc[i][0] = mfma32(af[slot][i], bf[slot][0], acc[i][0]);
;           acc[i][1] = mfma32(af[slot][i], bf[slot][1], acc[i][1]);
;           __builtin_amdgcn_sched_barrier(0);
;           if (pre && (i & 1) == 0) {
;             const int pi = ks * 2 + (i >> 1);
;             if (pi < 4) glds16(Ag0 + (size_t)pi * 64 * LDK + (kt + 1) * 64, st + (srow + 64 * pi) * 64 + sch * 8);
;             else glds16(Bg0 + (size_t)(pi - 4) * 64 * LDK + (kt + 1) * 64, st + 16384 + (srow + 64 * (pi - 4)) * 64 + sch * 8);
;             __builtin_amdgcn_sched_barrier(0);
;           }
;         }
;         if (ks + 2 < 4) { ldfrag(ks + 2, slot); __builtin_amdgcn_sched_barrier(0); }
;       }
	s_add_i32 s15, s11, 0xffff8000
	s_and_b32 s15, s15, 0x8000
	s_lshl_b32 s15, s15, 1
	v_lshl_or_b32 v128, v143, 1, s15
	v_lshl_add_u32 v149, v147, 1, s15
	s_and_b32 s98, s11, 0x8000
	s_lshl_b32 s98, s98, 1
	s_waitcnt lgkmcnt(7)
	v_mfma_f32_32x32x16_bf16 v[112:127], v[178:181], v[194:197], v[112:127]
	v_add3_u32 v226, s98, v162, v156
	s_waitcnt lgkmcnt(6)
	v_mfma_f32_32x32x16_bf16 v[96:111], v[178:181], v[198:201], v[96:111]
	v_readfirstlane_b32 s100, v226
	s_mov_b32 s16, m0
	s_add_i32 m0, s100, 0x8000
	s_nop 0
	global_load_lds_dwordx4 v[160:161], off
	v_mfma_f32_32x32x16_bf16 v[80:95], v[182:185], v[194:197], v[80:95]
	v_lshl_add_u64 v[178:179], v[160:161], 0, s[2:3]
	s_add_i32 m0, s100, 0xa000
	s_nop 0
	global_load_lds_dwordx4 v[178:179], off
	v_mfma_f32_32x32x16_bf16 v[64:79], v[182:185], v[198:201], v[64:79]
	v_lshl_add_u64 v[180:181], v[160:161], 0, s[4:5]
	s_add_i32 m0, s100, 0xc000
	s_nop 0
	global_load_lds_dwordx4 v[180:181], off
	v_mfma_f32_32x32x16_bf16 v[48:63], v[186:189], v[194:197], v[48:63]
	v_lshl_add_u64 v[178:179], v[160:161], 0, s[6:7]
	s_add_i32 m0, s100, 0xe000
	s_nop 0
	global_load_lds_dwordx4 v[178:179], off
	s_mov_b32 m0, s16
	v_mfma_f32_32x32x16_bf16 v[32:47], v[186:189], v[198:201], v[32:47]
	v_mfma_f32_32x32x16_bf16 v[16:31], v[190:193], v[194:197], v[16:31]
	v_mfma_f32_32x32x16_bf16 v[0:15], v[190:193], v[198:201], v[0:15]
	v_lshl_add_u64 v[160:161], v[160:161], 0, s[8:9]
	v_add_u32_e32 v177, v128, v175
	ds_read_b128 v[178:181], v177
	ds_read_b128 v[182:185], v177 offset:4096
	ds_read_b128 v[186:189], v177 offset:8192
	ds_read_b128 v[190:193], v177 offset:12288
	v_add_u32_e32 v177, v149, v175
	ds_read_b128 v[194:197], v177 offset:32768
	ds_read_b128 v[198:201], v177 offset:36864
	s_waitcnt lgkmcnt(7)
	v_mfma_f32_32x32x16_bf16 v[112:127], v[202:205], v[218:221], v[112:127]
	s_waitcnt lgkmcnt(6)
	v_mfma_f32_32x32x16_bf16 v[96:111], v[202:205], v[222:225], v[96:111]
	v_mfma_f32_32x32x16_bf16 v[80:95], v[206:209], v[218:221], v[80:95]
	v_mfma_f32_32x32x16_bf16 v[64:79], v[206:209], v[222:225], v[64:79]
	v_mfma_f32_32x32x16_bf16 v[48:63], v[210:213], v[218:221], v[48:63]
	v_mfma_f32_32x32x16_bf16 v[32:47], v[210:213], v[222:225], v[32:47]
	v_mfma_f32_32x32x16_bf16 v[16:31], v[214:217], v[218:221], v[16:31]
	v_mfma_f32_32x32x16_bf16 v[0:15], v[214:217], v[222:225], v[0:15]
	v_add_u32_e32 v128, v128, v176
	ds_read_b128 v[202:205], v128
	ds_read_b128 v[206:209], v128 offset:4096
	ds_read_b128 v[210:213], v128 offset:8192
	ds_read_b128 v[214:217], v128 offset:12288
	v_add_u32_e32 v128, v149, v176
	ds_read_b128 v[218:221], v128 offset:32768
	ds_read_b128 v[222:225], v128 offset:36864
	v_readlane_b32 s98, v254, 28
	v_readlane_b32 s99, v254, 24
	s_nop 1
	s_add_i32 s98, s34, s98
	s_lshr_b32 s100, s98, 5
	s_lshl_b32 s101, s100, 3
	s_or_b32 s101, s101, s99
	s_cmp_lt_i32 s101, 32
	s_cselect_b32 s98, s98, s34
	s_lshr_b32 s100, s98, 5
	s_and_b32 s101, s98, 31
	s_lshl_b32 s100, s100, 3
	s_or_b32 s100, s100, s99
	s_and_b32 s99, s101, 3
	s_lshl_b32 s100, s100, 2
	s_or_b32 s100, s100, s99
	s_ashr_i32 s101, s101, 2
	v_lshrrev_b32_e32 v236, 6, v252
	v_and_b32_e32 v237, 3, v236
	v_lshl_add_u32 v237, v237, 6, v135
	v_mov_b32_e32 v238, s101
	v_mov_b32_e32 v239, s100
	v_cmp_gt_u32_e32 vcc, 4, v236
	v_readlane_b32 s98, v253, 29
	v_readlane_b32 s99, v253, 30
	v_readlane_b32 s100, v253, 35
	v_readlane_b32 s101, v253, 36
	v_cndmask_b32_e32 v238, v238, v239, vcc
	v_lshl_add_u32 v237, v238, 8, v237
	v_mov_b32_e32 v240, s100
	v_mov_b32_e32 v241, s101
	v_mov_b32_e32 v242, s98
	v_mov_b32_e32 v243, s99
	v_cndmask_b32_e32 v240, v240, v242, vcc
	v_cndmask_b32_e32 v241, v241, v243, vcc
	v_mad_u64_u32 v[240:241], s[98:99], v237, s0, v[240:241]
	global_load_dword v236, v[240:241], off
	global_load_dword v237, v[240:241], off offset:128
	global_load_dword v244, v[240:241], off offset:256
	global_load_dword v245, v[240:241], off offset:384
	s_waitcnt lgkmcnt(7)
	v_mfma_f32_32x32x16_bf16 v[112:127], v[178:181], v[194:197], v[112:127]
	s_waitcnt lgkmcnt(6)
	v_mfma_f32_32x32x16_bf16 v[96:111], v[178:181], v[198:201], v[96:111]
	v_mfma_f32_32x32x16_bf16 v[80:95], v[182:185], v[194:197], v[80:95]
	v_mfma_f32_32x32x16_bf16 v[64:79], v[182:185], v[198:201], v[64:79]
	v_mfma_f32_32x32x16_bf16 v[48:63], v[186:189], v[194:197], v[48:63]
	v_mfma_f32_32x32x16_bf16 v[32:47], v[186:189], v[198:201], v[32:47]
	v_mfma_f32_32x32x16_bf16 v[16:31], v[190:193], v[194:197], v[16:31]
	v_mfma_f32_32x32x16_bf16 v[0:15], v[190:193], v[198:201], v[0:15]
	s_waitcnt lgkmcnt(1)
	v_mfma_f32_32x32x16_bf16 v[112:127], v[202:205], v[218:221], v[112:127]
	s_waitcnt lgkmcnt(0)
	v_mfma_f32_32x32x16_bf16 v[96:111], v[202:205], v[222:225], v[96:111]
	v_mfma_f32_32x32x16_bf16 v[80:95], v[206:209], v[218:221], v[80:95]
	v_mfma_f32_32x32x16_bf16 v[64:79], v[206:209], v[222:225], v[64:79]
	v_mfma_f32_32x32x16_bf16 v[48:63], v[210:213], v[218:221], v[48:63]
	v_mfma_f32_32x32x16_bf16 v[32:47], v[210:213], v[222:225], v[32:47]
	v_mfma_f32_32x32x16_bf16 v[16:31], v[214:217], v[218:221], v[16:31]
	v_mfma_f32_32x32x16_bf16 v[0:15], v[214:217], v[222:225], v[0:15]
	s_waitcnt vmcnt(4)
	s_barrier
; __device__ __forceinline__ int accrow(int reg, int lh) { return (reg & 3) + 8 * (reg >> 2) + 4 * lh; }
; template <int EPI, int PN>
; __device__ void gemm_phase(const Params& p, const u16* __restrict__ A, const u16* __restrict__ Bt, int nNt, char* smem) {
;     ...
;       ldfrag(0, 0);
;       ldfrag(1, 1);
;       __builtin_amdgcn_sched_barrier(0);
; #pragma unroll
;       for (int ks = 0; ks < 4; ++ks) {
;         const int slot = ks & 1;
; #pragma unroll
;         for (int i = 0; i < 4; ++i) {
;           acc[i][0] = mfma32(af[slot][i], bf[slot][0], acc[i][0]);
;           acc[i][1] = mfma32(af[slot][i], bf[slot][1], acc[i][1]);
;           __builtin_amdgcn_sched_barrier(0);
;           if (pre && (i & 1) == 0) {
;             const int pi = ks * 2 + (i >> 1);
;             if (pi < 4) glds16(Ag0 + (size_t)pi * 64 * LDK + (kt + 1) * 64, st + (srow + 64 * pi) * 64 + sch * 8);
;             else glds16(Bg0 + (size_t)(pi - 4) * 64 * LDK + (kt + 1) * 64, st + 16384 + (srow + 64 * (pi - 4)) * 64 + sch * 8);
;             __builtin_amdgcn_sched_barrier(0);
;           }
;         }
;         if (ks + 2 < 4) { ldfrag(ks + 2, slot); __builtin_amdgcn_sched_barrier(0); }
;       }
;     }
;     __syncthreads();
;     ...
; #pragma unroll
;       for (int i = 0; i < 4; ++i)
; #pragma unroll
;         for (int j = 0; j < 2; ++j)
; #pragma unroll
;           for (int r = 0; r < 16; ++r) *(u16*)(et + (i * 32 + accrow(r, lhE)) * 144 + (j * 32 + lrE) * 2) = f2bf(acc[i][j][r]);
	ds_read_b128 v[158:161], v164
	ds_read_b128 v[178:181], v164 offset:4096
	ds_read_b128 v[182:185], v164 offset:8192
	ds_read_b128 v[186:189], v164 offset:12288
	ds_read_b128 v[190:193], v165
	ds_read_b128 v[194:197], v165 offset:4096
	ds_read_b128 v[198:201], v166
	ds_read_b128 v[202:205], v166 offset:4096
	ds_read_b128 v[206:209], v166 offset:8192
	ds_read_b128 v[210:213], v166 offset:12288
	ds_read_b128 v[214:217], v168
	ds_read_b128 v[218:221], v168 offset:4096
	s_waitcnt lgkmcnt(7)
	v_mfma_f32_32x32x16_bf16 v[112:127], v[158:161], v[190:193], v[112:127]
	s_waitcnt lgkmcnt(6)
	v_mfma_f32_32x32x16_bf16 v[96:111], v[158:161], v[194:197], v[96:111]
	v_mfma_f32_32x32x16_bf16 v[80:95], v[178:181], v[190:193], v[80:95]
	v_mfma_f32_32x32x16_bf16 v[64:79], v[178:181], v[194:197], v[64:79]
	v_mfma_f32_32x32x16_bf16 v[48:63], v[182:185], v[190:193], v[48:63]
	v_mfma_f32_32x32x16_bf16 v[32:47], v[182:185], v[194:197], v[32:47]
	v_mfma_f32_32x32x16_bf16 v[16:31], v[186:189], v[190:193], v[16:31]
	v_mfma_f32_32x32x16_bf16 v[0:15], v[186:189], v[194:197], v[0:15]
	ds_read_b128 v[158:161], v169
	ds_read_b128 v[178:181], v169 offset:4096
	ds_read_b128 v[182:185], v169 offset:8192
	ds_read_b128 v[186:189], v169 offset:12288
	ds_read_b128 v[190:193], v170
	ds_read_b128 v[194:197], v170 offset:4096
	s_waitcnt lgkmcnt(7)
	v_mfma_f32_32x32x16_bf16 v[112:127], v[198:201], v[214:217], v[112:127]
	s_waitcnt lgkmcnt(6)
	v_mfma_f32_32x32x16_bf16 v[96:111], v[198:201], v[218:221], v[96:111]
	v_mfma_f32_32x32x16_bf16 v[80:95], v[202:205], v[214:217], v[80:95]
	v_mfma_f32_32x32x16_bf16 v[64:79], v[202:205], v[218:221], v[64:79]
	v_mfma_f32_32x32x16_bf16 v[48:63], v[206:209], v[214:217], v[48:63]
	v_mfma_f32_32x32x16_bf16 v[32:47], v[206:209], v[218:221], v[32:47]
	v_mfma_f32_32x32x16_bf16 v[16:31], v[210:213], v[214:217], v[16:31]
	v_mfma_f32_32x32x16_bf16 v[0:15], v[210:213], v[218:221], v[0:15]
	ds_read_b128 v[198:201], v171
	ds_read_b128 v[202:205], v171 offset:4096
	ds_read_b128 v[206:209], v171 offset:8192
	ds_read_b128 v[210:213], v171 offset:12288
	ds_read_b128 v[214:217], v172
	ds_read_b128 v[218:221], v172 offset:4096
	s_waitcnt lgkmcnt(7)
	v_mfma_f32_32x32x16_bf16 v[112:127], v[158:161], v[190:193], v[112:127]
	s_waitcnt lgkmcnt(6)
	v_mfma_f32_32x32x16_bf16 v[96:111], v[158:161], v[194:197], v[96:111]
	v_mfma_f32_32x32x16_bf16 v[80:95], v[178:181], v[190:193], v[80:95]
	v_mfma_f32_32x32x16_bf16 v[64:79], v[178:181], v[194:197], v[64:79]
	v_mfma_f32_32x32x16_bf16 v[48:63], v[182:185], v[190:193], v[48:63]
	v_mfma_f32_32x32x16_bf16 v[32:47], v[182:185], v[194:197], v[32:47]
	v_mfma_f32_32x32x16_bf16 v[16:31], v[186:189], v[190:193], v[16:31]
	v_mfma_f32_32x32x16_bf16 v[0:15], v[186:189], v[194:197], v[0:15]
	s_waitcnt lgkmcnt(1)
	v_mfma_f32_32x32x16_bf16 v[112:127], v[198:201], v[214:217], v[112:127]
	s_waitcnt lgkmcnt(0)
	v_mfma_f32_32x32x16_bf16 v[96:111], v[198:201], v[218:221], v[96:111]
	v_mfma_f32_32x32x16_bf16 v[80:95], v[202:205], v[214:217], v[80:95]
	v_mfma_f32_32x32x16_bf16 v[64:79], v[202:205], v[218:221], v[64:79]
	v_mfma_f32_32x32x16_bf16 v[48:63], v[206:209], v[214:217], v[48:63]
	v_mfma_f32_32x32x16_bf16 v[32:47], v[206:209], v[218:221], v[32:47]
	v_mfma_f32_32x32x16_bf16 v[16:31], v[210:213], v[214:217], v[16:31]
	v_mfma_f32_32x32x16_bf16 v[0:15], v[210:213], v[218:221], v[0:15]
	v_mov_b32_e32 v149, v135
	v_mov_b32_e32 v128, v139
	v_mov_b32_e32 v158, v137
	s_barrier
	s_nop 7
	v_cvt_pk_bf16_f32 v0, v0, s0
	v_lshlrev_b32_e32 v158, 1, v158
	v_mul_lo_u32 v128, v128, s12
	v_add3_u32 v128, v163, v158, v128
	v_cvt_pk_bf16_f32 v112, v112, s0
	v_cvt_pk_bf16_f32 v96, v96, s0
	v_cvt_pk_bf16_f32 v80, v80, s0
	v_cvt_pk_bf16_f32 v64, v64, s0
	v_cvt_pk_bf16_f32 v48, v48, s0
	v_cvt_pk_bf16_f32 v32, v32, s0
	v_cvt_pk_bf16_f32 v16, v16, s0
	ds_write_b16 v128, v0 offset:13888
	v_cvt_pk_bf16_f32 v0, v1, s0
	ds_write_b16 v128, v112
	v_cvt_pk_bf16_f32 v112, v113, s0
	ds_write_b16 v128, v96 offset:64
	v_cvt_pk_bf16_f32 v96, v97, s0
	ds_write_b16 v128, v80 offset:4608
	v_cvt_pk_bf16_f32 v80, v81, s0
	ds_write_b16 v128, v64 offset:4672
	v_cvt_pk_bf16_f32 v64, v65, s0
	ds_write_b16 v128, v48 offset:9216
	v_cvt_pk_bf16_f32 v48, v49, s0
	ds_write_b16 v128, v32 offset:9280
	v_cvt_pk_bf16_f32 v32, v33, s0
	ds_write_b16 v128, v16 offset:13824
	v_cvt_pk_bf16_f32 v16, v17, s0
	ds_write_b16 v128, v0 offset:14032
	v_cvt_pk_bf16_f32 v0, v2, s0
	ds_write_b16 v128, v112 offset:144
	v_cvt_pk_bf16_f32 v112, v114, s0
	ds_write_b16 v128, v96 offset:208
	v_cvt_pk_bf16_f32 v96, v98, s0
	ds_write_b16 v128, v80 offset:4752
	v_cvt_pk_bf16_f32 v80, v82, s0
	ds_write_b16 v128, v64 offset:4816
	v_cvt_pk_bf16_f32 v64, v66, s0
	ds_write_b16 v128, v48 offset:9360
	v_cvt_pk_bf16_f32 v48, v50, s0
	ds_write_b16 v128, v32 offset:9424
	v_cvt_pk_bf16_f32 v32, v34, s0
	ds_write_b16 v128, v16 offset:13968
	v_cvt_pk_bf16_f32 v16, v18, s0
	ds_write_b16 v128, v0 offset:14176
	v_cvt_pk_bf16_f32 v0, v3, s0
	ds_write_b16 v128, v112 offset:288
	v_cvt_pk_bf16_f32 v112, v115, s0
	ds_write_b16 v128, v96 offset:352
	v_cvt_pk_bf16_f32 v96, v99, s0
	ds_write_b16 v128, v80 offset:4896
	v_cvt_pk_bf16_f32 v80, v83, s0
	ds_write_b16 v128, v64 offset:4960
	v_cvt_pk_bf16_f32 v64, v67, s0
	ds_write_b16 v128, v48 offset:9504
	v_cvt_pk_bf16_f32 v48, v51, s0
	ds_write_b16 v128, v32 offset:9568
	v_cvt_pk_bf16_f32 v32, v35, s0
	ds_write_b16 v128, v16 offset:14112
	v_cvt_pk_bf16_f32 v16, v19, s0
	ds_write_b16 v128, v0 offset:14320
	v_cvt_pk_bf16_f32 v0, v4, s0
	ds_write_b16 v128, v112 offset:432
	v_cvt_pk_bf16_f32 v112, v116, s0
	ds_write_b16 v128, v96 offset:496
	v_cvt_pk_bf16_f32 v96, v100, s0
	ds_write_b16 v128, v80 offset:5040
; __device__ __forceinline__ int accrow(int reg, int lh) { return (reg & 3) + 8 * (reg >> 2) + 4 * lh; }
; template <int EPI, int PN>
; __device__ void gemm_phase(const Params& p, const u16* __restrict__ A, const u16* __restrict__ Bt, int nNt, char* smem) {
;     ...
; #pragma unroll
;       for (int i = 0; i < 4; ++i)
; #pragma unroll
;         for (int j = 0; j < 2; ++j)
; #pragma unroll
;           for (int r = 0; r < 16; ++r) *(u16*)(et + (i * 32 + accrow(r, lhE)) * 144 + (j * 32 + lrE) * 2) = f2bf(acc[i][j][r]);
	v_cvt_pk_bf16_f32 v80, v84, s0
	ds_write_b16 v128, v64 offset:5104
	v_cvt_pk_bf16_f32 v64, v68, s0
	ds_write_b16 v128, v48 offset:9648
	v_cvt_pk_bf16_f32 v48, v52, s0
	ds_write_b16 v128, v32 offset:9712
	v_cvt_pk_bf16_f32 v32, v36, s0
	ds_write_b16 v128, v16 offset:14256
	v_cvt_pk_bf16_f32 v16, v20, s0
	ds_write_b16 v128, v0 offset:15040
	v_cvt_pk_bf16_f32 v0, v5, s0
	ds_write_b16 v128, v112 offset:1152
	v_cvt_pk_bf16_f32 v112, v117, s0
	ds_write_b16 v128, v96 offset:1216
	v_cvt_pk_bf16_f32 v96, v101, s0
	ds_write_b16 v128, v80 offset:5760
	v_cvt_pk_bf16_f32 v80, v85, s0
	ds_write_b16 v128, v64 offset:5824
	v_cvt_pk_bf16_f32 v64, v69, s0
	ds_write_b16 v128, v48 offset:10368
	v_cvt_pk_bf16_f32 v48, v53, s0
	ds_write_b16 v128, v32 offset:10432
	v_cvt_pk_bf16_f32 v32, v37, s0
	ds_write_b16 v128, v16 offset:14976
	v_cvt_pk_bf16_f32 v16, v21, s0
	ds_write_b16 v128, v0 offset:15184
	v_cvt_pk_bf16_f32 v0, v6, s0
	ds_write_b16 v128, v112 offset:1296
	v_cvt_pk_bf16_f32 v112, v118, s0
	ds_write_b16 v128, v96 offset:1360
	v_cvt_pk_bf16_f32 v96, v102, s0
	ds_write_b16 v128, v80 offset:5904
	v_cvt_pk_bf16_f32 v80, v86, s0
	ds_write_b16 v128, v64 offset:5968
	v_cvt_pk_bf16_f32 v64, v70, s0
	ds_write_b16 v128, v48 offset:10512
	v_cvt_pk_bf16_f32 v48, v54, s0
	ds_write_b16 v128, v32 offset:10576
	v_cvt_pk_bf16_f32 v32, v38, s0
	ds_write_b16 v128, v16 offset:15120
	v_cvt_pk_bf16_f32 v16, v22, s0
	ds_write_b16 v128, v0 offset:15328
	v_cvt_pk_bf16_f32 v0, v7, s0
	ds_write_b16 v128, v112 offset:1440
	v_cvt_pk_bf16_f32 v112, v119, s0
	ds_write_b16 v128, v96 offset:1504
	v_cvt_pk_bf16_f32 v96, v103, s0
	ds_write_b16 v128, v80 offset:6048
	v_cvt_pk_bf16_f32 v80, v87, s0
	ds_write_b16 v128, v64 offset:6112
	v_cvt_pk_bf16_f32 v64, v71, s0
	ds_write_b16 v128, v48 offset:10656
	v_cvt_pk_bf16_f32 v48, v55, s0
	ds_write_b16 v128, v32 offset:10720
	v_cvt_pk_bf16_f32 v32, v39, s0
	ds_write_b16 v128, v16 offset:15264
	v_cvt_pk_bf16_f32 v16, v23, s0
	ds_write_b16 v128, v0 offset:15472
	v_cvt_pk_bf16_f32 v0, v8, s0
	ds_write_b16 v128, v112 offset:1584
	v_cvt_pk_bf16_f32 v112, v120, s0
	ds_write_b16 v128, v96 offset:1648
	v_cvt_pk_bf16_f32 v96, v104, s0
	ds_write_b16 v128, v80 offset:6192
	v_cvt_pk_bf16_f32 v80, v88, s0
	ds_write_b16 v128, v64 offset:6256
	v_cvt_pk_bf16_f32 v64, v72, s0
	ds_write_b16 v128, v48 offset:10800
	v_cvt_pk_bf16_f32 v48, v56, s0
	ds_write_b16 v128, v32 offset:10864
	v_cvt_pk_bf16_f32 v32, v40, s0
	ds_write_b16 v128, v16 offset:15408
	v_cvt_pk_bf16_f32 v16, v24, s0
	ds_write_b16 v128, v0 offset:16192
	v_cvt_pk_bf16_f32 v0, v9, s0
	ds_write_b16 v128, v112 offset:2304
	v_cvt_pk_bf16_f32 v112, v121, s0
	ds_write_b16 v128, v96 offset:2368
	v_cvt_pk_bf16_f32 v96, v105, s0
	ds_write_b16 v128, v80 offset:6912
	v_cvt_pk_bf16_f32 v80, v89, s0
	ds_write_b16 v128, v64 offset:6976
	v_cvt_pk_bf16_f32 v64, v73, s0
	ds_write_b16 v128, v48 offset:11520
	v_cvt_pk_bf16_f32 v48, v57, s0
	ds_write_b16 v128, v32 offset:11584
	v_cvt_pk_bf16_f32 v32, v41, s0
	ds_write_b16 v128, v16 offset:16128
	v_cvt_pk_bf16_f32 v16, v25, s0
	ds_write_b16 v128, v0 offset:16336
	v_cvt_pk_bf16_f32 v0, v10, s0
	ds_write_b16 v128, v112 offset:2448
	v_cvt_pk_bf16_f32 v112, v122, s0
	ds_write_b16 v128, v96 offset:2512
	v_cvt_pk_bf16_f32 v96, v106, s0
	ds_write_b16 v128, v80 offset:7056
	v_cvt_pk_bf16_f32 v80, v90, s0
	ds_write_b16 v128, v64 offset:7120
	v_cvt_pk_bf16_f32 v64, v74, s0
	ds_write_b16 v128, v48 offset:11664
	v_cvt_pk_bf16_f32 v48, v58, s0
	ds_write_b16 v128, v32 offset:11728
	v_cvt_pk_bf16_f32 v32, v42, s0
	ds_write_b16 v128, v16 offset:16272
	v_cvt_pk_bf16_f32 v16, v26, s0
	ds_write_b16 v128, v0 offset:16480
	v_cvt_pk_bf16_f32 v0, v11, s0
	ds_write_b16 v128, v112 offset:2592
	v_cvt_pk_bf16_f32 v112, v123, s0
	ds_write_b16 v128, v96 offset:2656
	v_cvt_pk_bf16_f32 v96, v107, s0
	ds_write_b16 v128, v80 offset:7200
	v_cvt_pk_bf16_f32 v80, v91, s0
	ds_write_b16 v128, v64 offset:7264
	v_cvt_pk_bf16_f32 v64, v75, s0
	ds_write_b16 v128, v48 offset:11808
	v_cvt_pk_bf16_f32 v48, v59, s0
	ds_write_b16 v128, v32 offset:11872
	v_cvt_pk_bf16_f32 v32, v43, s0
	ds_write_b16 v128, v16 offset:16416
	v_cvt_pk_bf16_f32 v16, v27, s0
	ds_write_b16 v128, v0 offset:16624
	v_cvt_pk_bf16_f32 v0, v12, s0
	ds_write_b16 v128, v112 offset:2736
	v_cvt_pk_bf16_f32 v112, v124, s0
	ds_write_b16 v128, v96 offset:2800
	v_cvt_pk_bf16_f32 v96, v108, s0
	ds_write_b16 v128, v80 offset:7344
	v_cvt_pk_bf16_f32 v80, v92, s0
	ds_write_b16 v128, v64 offset:7408
	v_cvt_pk_bf16_f32 v64, v76, s0
	ds_write_b16 v128, v48 offset:11952
	v_cvt_pk_bf16_f32 v48, v60, s0
	ds_write_b16 v128, v32 offset:12016
	v_cvt_pk_bf16_f32 v32, v44, s0
	ds_write_b16 v128, v16 offset:16560
	v_cvt_pk_bf16_f32 v16, v28, s0
	ds_write_b16 v128, v0 offset:17344
	v_cvt_pk_bf16_f32 v0, v13, s0
	ds_write_b16 v128, v112 offset:3456
	v_cvt_pk_bf16_f32 v112, v125, s0
	ds_write_b16 v128, v96 offset:3520
	v_cvt_pk_bf16_f32 v96, v109, s0
	ds_write_b16 v128, v80 offset:8064
	v_cvt_pk_bf16_f32 v80, v93, s0
	ds_write_b16 v128, v64 offset:8128
	v_cvt_pk_bf16_f32 v64, v77, s0
	ds_write_b16 v128, v48 offset:12672
	v_cvt_pk_bf16_f32 v48, v61, s0
	ds_write_b16 v128, v32 offset:12736
	v_cvt_pk_bf16_f32 v32, v45, s0
	ds_write_b16 v128, v16 offset:17280
	v_cvt_pk_bf16_f32 v16, v29, s0
	ds_write_b16 v128, v0 offset:17488
	v_cvt_pk_bf16_f32 v0, v14, s0
	ds_write_b16 v128, v112 offset:3600
	v_cvt_pk_bf16_f32 v112, v126, s0
	ds_write_b16 v128, v96 offset:3664
	v_cvt_pk_bf16_f32 v96, v110, s0
	ds_write_b16 v128, v80 offset:8208
	v_cvt_pk_bf16_f32 v80, v94, s0
	ds_write_b16 v128, v64 offset:8272
	v_cvt_pk_bf16_f32 v64, v78, s0
	ds_write_b16 v128, v48 offset:12816
; __device__ __forceinline__ int accrow(int reg, int lh) { return (reg & 3) + 8 * (reg >> 2) + 4 * lh; }
; template <int EPI, int PN>
; __device__ void gemm_phase(const Params& p, const u16* __restrict__ A, const u16* __restrict__ Bt, int nNt, char* smem) {
;     ...
;           for (int r = 0; r < 16; ++r) *(u16*)(et + (i * 32 + accrow(r, lhE)) * 144 + (j * 32 + lrE) * 2) = f2bf(acc[i][j][r]);
; #pragma unroll
;       for (int it = 0; it < 16; ++it) {
;         const int c = it * 64 + laneE, row = c >> 3, seg = c & 7;
;         const uint4 v = *(const uint4*)(et + row * 144 + seg * 16);
;         if (EPI == 0) *(uint4*)(p.proj + (row0 + row) * NPROJ + col0 + seg * 8) = v;
;         else *(uint4*)(p.qp + (row0 + row) * DM + col0 + seg * 8) = v;
	v_cvt_pk_bf16_f32 v48, v62, s0
	ds_write_b16 v128, v32 offset:12880
	v_cvt_pk_bf16_f32 v32, v46, s0
	ds_write_b16 v128, v16 offset:17424
	v_cvt_pk_bf16_f32 v16, v30, s0
	ds_write_b16 v128, v0 offset:17632
	v_cvt_pk_bf16_f32 v0, v15, s0
	s_ashr_i32 s11, s10, 31
	ds_write_b16 v128, v112 offset:3744
	v_cvt_pk_bf16_f32 v112, v127, s0
	ds_write_b16 v128, v96 offset:3808
	v_cvt_pk_bf16_f32 v96, v111, s0
	ds_write_b16 v128, v80 offset:8352
	v_cvt_pk_bf16_f32 v80, v95, s0
	ds_write_b16 v128, v64 offset:8416
	v_cvt_pk_bf16_f32 v64, v79, s0
	ds_write_b16 v128, v48 offset:12960
	v_cvt_pk_bf16_f32 v48, v63, s0
	ds_write_b16 v128, v32 offset:13024
	v_cvt_pk_bf16_f32 v32, v47, s0
	ds_write_b16 v128, v16 offset:17568
	v_cvt_pk_bf16_f32 v16, v31, s0
	ds_write_b16 v128, v0 offset:17776
	v_lshlrev_b32_e32 v0, 4, v149
	s_lshl_b64 s[10:11], s[10:11], 8
	ds_write_b16 v128, v112 offset:3888
	ds_write_b16 v128, v96 offset:3952
	ds_write_b16 v128, v80 offset:8496
	ds_write_b16 v128, v64 offset:8560
	ds_write_b16 v128, v48 offset:13104
	ds_write_b16 v128, v32 offset:13168
	ds_write_b16 v128, v16 offset:17712
	v_and_b32_e32 v128, 0x70, v0
	v_ashrrev_i32_e32 v6, 3, v149
	v_mov_b32_e32 v9, s11
	v_or_b32_e32 v8, s10, v134
	v_add_u32_e32 v10, v163, v128
	v_ashrrev_i32_e32 v7, 31, v6
	v_lshl_add_u32 v4, s14, 8, v145
	v_mad_u64_u32 v[0:1], s[10:11], v6, s13, v[10:11]
	v_lshl_add_u64 v[6:7], v[8:9], 0, v[6:7]
	v_readlane_b32 s16, v253, 39
	v_ashrrev_i32_e32 v5, 31, v4
	v_lshlrev_b64 v[6:7], 12, v[6:7]
	v_readlane_b32 s26, v253, 49
	v_readlane_b32 s27, v253, 50
	ds_read_b128 v[0:3], v0
	v_lshlrev_b64 v[12:13], 1, v[4:5]
	v_lshl_add_u64 v[6:7], s[26:27], 0, v[6:7]
	v_lshl_add_u64 v[4:5], v[6:7], 0, v[12:13]
	v_lshl_add_u64 v[14:15], v[4:5], 0, v[128:129]
	v_add_u32_e32 v4, 64, v149
	v_ashrrev_i32_e32 v16, 3, v4
	v_mad_u64_u32 v[4:5], s[10:11], v16, s13, v[10:11]
	v_ashrrev_i32_e32 v17, 31, v16
	ds_read_b128 v[4:7], v4
	s_waitcnt lgkmcnt(1)
	global_store_dwordx4 v[14:15], v[0:3], off
	v_readlane_b32 s17, v253, 40
	v_readlane_b32 s18, v253, 41
	v_lshl_add_u64 v[0:1], v[8:9], 0, v[16:17]
	v_lshlrev_b64 v[0:1], 12, v[0:1]
	v_lshl_add_u64 v[0:1], s[26:27], 0, v[0:1]
	v_lshl_add_u64 v[0:1], v[0:1], 0, v[12:13]
	v_lshl_add_u64 v[0:1], v[0:1], 0, v[128:129]
	s_waitcnt lgkmcnt(0)
	global_store_dwordx4 v[0:1], v[4:7], off
	v_add_u32_e32 v0, 0x80, v149
	v_readlane_b32 s19, v253, 42
	v_ashrrev_i32_e32 v4, 3, v0
	v_ashrrev_i32_e32 v5, 31, v4
	v_mad_u64_u32 v[0:1], s[10:11], v4, s13, v[10:11]
	v_lshl_add_u64 v[4:5], v[8:9], 0, v[4:5]
	v_lshlrev_b64 v[4:5], 12, v[4:5]
	ds_read_b128 v[0:3], v0
	v_lshl_add_u64 v[4:5], s[26:27], 0, v[4:5]
	v_lshl_add_u64 v[4:5], v[4:5], 0, v[12:13]
	v_lshl_add_u64 v[14:15], v[4:5], 0, v[128:129]
	v_add_u32_e32 v4, 0xc0, v149
	v_ashrrev_i32_e32 v16, 3, v4
	v_mad_u64_u32 v[4:5], s[10:11], v16, s13, v[10:11]
	v_ashrrev_i32_e32 v17, 31, v16
	ds_read_b128 v[4:7], v4
	s_waitcnt lgkmcnt(1)
	global_store_dwordx4 v[14:15], v[0:3], off
	v_readlane_b32 s20, v253, 43
	v_readlane_b32 s21, v253, 44
	v_lshl_add_u64 v[0:1], v[8:9], 0, v[16:17]
	v_lshlrev_b64 v[0:1], 12, v[0:1]
	v_lshl_add_u64 v[0:1], s[26:27], 0, v[0:1]
	v_lshl_add_u64 v[0:1], v[0:1], 0, v[12:13]
	v_lshl_add_u64 v[0:1], v[0:1], 0, v[128:129]
	s_waitcnt lgkmcnt(0)
	global_store_dwordx4 v[0:1], v[4:7], off
	v_add_u32_e32 v0, 0x100, v149
	v_readlane_b32 s22, v253, 45
	v_ashrrev_i32_e32 v4, 3, v0
	v_ashrrev_i32_e32 v5, 31, v4
	v_mad_u64_u32 v[0:1], s[10:11], v4, s13, v[10:11]
	v_lshl_add_u64 v[4:5], v[8:9], 0, v[4:5]
	v_lshlrev_b64 v[4:5], 12, v[4:5]
	ds_read_b128 v[0:3], v0
	v_lshl_add_u64 v[4:5], s[26:27], 0, v[4:5]
	v_lshl_add_u64 v[4:5], v[4:5], 0, v[12:13]
	v_lshl_add_u64 v[14:15], v[4:5], 0, v[128:129]
	v_add_u32_e32 v4, 0x140, v149
	v_ashrrev_i32_e32 v16, 3, v4
	v_mad_u64_u32 v[4:5], s[10:11], v16, s13, v[10:11]
	v_ashrrev_i32_e32 v17, 31, v16
	ds_read_b128 v[4:7], v4
	s_waitcnt lgkmcnt(1)
	global_store_dwordx4 v[14:15], v[0:3], off
	v_readlane_b32 s23, v253, 46
	v_readlane_b32 s24, v253, 47
	v_lshl_add_u64 v[0:1], v[8:9], 0, v[16:17]
	v_lshlrev_b64 v[0:1], 12, v[0:1]
	v_lshl_add_u64 v[0:1], s[26:27], 0, v[0:1]
	v_lshl_add_u64 v[0:1], v[0:1], 0, v[12:13]
	v_lshl_add_u64 v[0:1], v[0:1], 0, v[128:129]
	s_waitcnt lgkmcnt(0)
	global_store_dwordx4 v[0:1], v[4:7], off
	v_add_u32_e32 v0, 0x180, v149
	v_readlane_b32 s25, v253, 48
	v_ashrrev_i32_e32 v4, 3, v0
	v_ashrrev_i32_e32 v5, 31, v4
	v_mad_u64_u32 v[0:1], s[10:11], v4, s13, v[10:11]
	v_lshl_add_u64 v[4:5], v[8:9], 0, v[4:5]
	v_lshlrev_b64 v[4:5], 12, v[4:5]
	ds_read_b128 v[0:3], v0
	v_lshl_add_u64 v[4:5], s[26:27], 0, v[4:5]
	v_lshl_add_u64 v[4:5], v[4:5], 0, v[12:13]
	v_lshl_add_u64 v[14:15], v[4:5], 0, v[128:129]
	v_add_u32_e32 v4, 0x1c0, v149
	v_ashrrev_i32_e32 v16, 3, v4
	v_mad_u64_u32 v[4:5], s[10:11], v16, s13, v[10:11]
	v_ashrrev_i32_e32 v17, 31, v16
	ds_read_b128 v[4:7], v4
	s_waitcnt lgkmcnt(1)
; template <int EPI, int PN>
; __device__ void gemm_phase(const Params& p, const u16* __restrict__ A, const u16* __restrict__ Bt, int nNt, char* smem) {
;     ...
;   for (int q = jb;; q += NJ) {
;     const int pl = q / (4 * PN), w = q % (4 * PN);
;     const int gp = pl * 8 + xcd;
;     if (gp >= npatch) break;
;     ...
;       for (int it = 0; it < 16; ++it) {
;         const int c = it * 64 + laneE, row = c >> 3, seg = c & 7;
;         const uint4 v = *(const uint4*)(et + row * 144 + seg * 16);
;         if (EPI == 0) *(uint4*)(p.proj + (row0 + row) * NPROJ + col0 + seg * 8) = v;
;         else *(uint4*)(p.qp + (row0 + row) * DM + col0 + seg * 8) = v;
;       }
;     }
;     __syncthreads();
;   }
	global_store_dwordx4 v[14:15], v[0:3], off
	v_readlane_b32 s28, v253, 51
	v_readlane_b32 s29, v253, 52
	v_lshl_add_u64 v[0:1], v[8:9], 0, v[16:17]
	v_lshlrev_b64 v[0:1], 12, v[0:1]
	v_lshl_add_u64 v[0:1], s[26:27], 0, v[0:1]
	v_lshl_add_u64 v[0:1], v[0:1], 0, v[12:13]
	v_lshl_add_u64 v[0:1], v[0:1], 0, v[128:129]
	s_waitcnt lgkmcnt(0)
	global_store_dwordx4 v[0:1], v[4:7], off
	v_add_u32_e32 v0, 0x200, v149
	v_readlane_b32 s30, v253, 53
	v_ashrrev_i32_e32 v4, 3, v0
	v_ashrrev_i32_e32 v5, 31, v4
	v_mad_u64_u32 v[0:1], s[10:11], v4, s13, v[10:11]
	v_lshl_add_u64 v[4:5], v[8:9], 0, v[4:5]
	v_lshlrev_b64 v[4:5], 12, v[4:5]
	ds_read_b128 v[0:3], v0
	v_lshl_add_u64 v[4:5], s[26:27], 0, v[4:5]
	v_lshl_add_u64 v[4:5], v[4:5], 0, v[12:13]
	v_lshl_add_u64 v[14:15], v[4:5], 0, v[128:129]
	v_add_u32_e32 v4, 0x240, v149
	v_ashrrev_i32_e32 v16, 3, v4
	v_mad_u64_u32 v[4:5], s[10:11], v16, s13, v[10:11]
	v_ashrrev_i32_e32 v17, 31, v16
	ds_read_b128 v[4:7], v4
	s_waitcnt lgkmcnt(1)
	global_store_dwordx4 v[14:15], v[0:3], off
	v_readlane_b32 s31, v253, 54
	s_nop 0
	v_lshl_add_u64 v[0:1], v[8:9], 0, v[16:17]
	v_lshlrev_b64 v[0:1], 12, v[0:1]
	v_lshl_add_u64 v[0:1], s[26:27], 0, v[0:1]
	v_lshl_add_u64 v[0:1], v[0:1], 0, v[12:13]
	v_lshl_add_u64 v[0:1], v[0:1], 0, v[128:129]
	s_waitcnt lgkmcnt(0)
	global_store_dwordx4 v[0:1], v[4:7], off
	v_add_u32_e32 v0, 0x280, v149
	s_nop 0
	v_ashrrev_i32_e32 v4, 3, v0
	v_ashrrev_i32_e32 v5, 31, v4
	v_mad_u64_u32 v[0:1], s[10:11], v4, s13, v[10:11]
	v_lshl_add_u64 v[4:5], v[8:9], 0, v[4:5]
	v_lshlrev_b64 v[4:5], 12, v[4:5]
	ds_read_b128 v[0:3], v0
	v_lshl_add_u64 v[4:5], s[26:27], 0, v[4:5]
	v_lshl_add_u64 v[4:5], v[4:5], 0, v[12:13]
	v_lshl_add_u64 v[14:15], v[4:5], 0, v[128:129]
	v_add_u32_e32 v4, 0x2c0, v149
	v_ashrrev_i32_e32 v16, 3, v4
	v_mad_u64_u32 v[4:5], s[10:11], v16, s13, v[10:11]
	v_ashrrev_i32_e32 v17, 31, v16
	ds_read_b128 v[4:7], v4
	s_waitcnt lgkmcnt(1)
	global_store_dwordx4 v[14:15], v[0:3], off
	s_nop 1
	v_lshl_add_u64 v[0:1], v[8:9], 0, v[16:17]
	v_lshlrev_b64 v[0:1], 12, v[0:1]
	v_lshl_add_u64 v[0:1], s[26:27], 0, v[0:1]
	v_lshl_add_u64 v[0:1], v[0:1], 0, v[12:13]
	v_lshl_add_u64 v[0:1], v[0:1], 0, v[128:129]
	s_waitcnt lgkmcnt(0)
	global_store_dwordx4 v[0:1], v[4:7], off
	v_add_u32_e32 v0, 0x300, v149
	s_nop 0
	v_ashrrev_i32_e32 v4, 3, v0
	v_ashrrev_i32_e32 v5, 31, v4
	v_mad_u64_u32 v[0:1], s[10:11], v4, s13, v[10:11]
	v_lshl_add_u64 v[4:5], v[8:9], 0, v[4:5]
	v_lshlrev_b64 v[4:5], 12, v[4:5]
	ds_read_b128 v[0:3], v0
	v_lshl_add_u64 v[4:5], s[26:27], 0, v[4:5]
	v_lshl_add_u64 v[4:5], v[4:5], 0, v[12:13]
	v_lshl_add_u64 v[14:15], v[4:5], 0, v[128:129]
	v_add_u32_e32 v4, 0x340, v149
	v_ashrrev_i32_e32 v16, 3, v4
	v_mad_u64_u32 v[4:5], s[10:11], v16, s13, v[10:11]
	v_ashrrev_i32_e32 v17, 31, v16
	ds_read_b128 v[4:7], v4
	s_waitcnt lgkmcnt(1)
	global_store_dwordx4 v[14:15], v[0:3], off
	s_nop 1
	v_lshl_add_u64 v[0:1], v[8:9], 0, v[16:17]
	v_lshlrev_b64 v[0:1], 12, v[0:1]
	v_lshl_add_u64 v[0:1], s[26:27], 0, v[0:1]
	v_lshl_add_u64 v[0:1], v[0:1], 0, v[12:13]
	v_lshl_add_u64 v[0:1], v[0:1], 0, v[128:129]
	s_waitcnt lgkmcnt(0)
	global_store_dwordx4 v[0:1], v[4:7], off
	v_add_u32_e32 v0, 0x380, v149
	s_nop 0
	v_ashrrev_i32_e32 v4, 3, v0
	v_ashrrev_i32_e32 v5, 31, v4
	v_mad_u64_u32 v[0:1], s[10:11], v4, s13, v[10:11]
	v_lshl_add_u64 v[4:5], v[8:9], 0, v[4:5]
	v_lshlrev_b64 v[4:5], 12, v[4:5]
	v_lshl_add_u64 v[4:5], s[26:27], 0, v[4:5]
	v_lshl_add_u64 v[4:5], v[4:5], 0, v[12:13]
	v_lshl_add_u64 v[14:15], v[4:5], 0, v[128:129]
	v_add_u32_e32 v4, 0x3c0, v149
	v_ashrrev_i32_e32 v16, 3, v4
	ds_read_b128 v[0:3], v0
	v_mad_u64_u32 v[4:5], s[10:11], v16, s13, v[10:11]
	v_readlane_b32 s10, v254, 28
	s_add_i32 s34, s34, s10
	s_ashr_i32 s10, s34, 31
	v_ashrrev_i32_e32 v17, 31, v16
	s_lshr_b32 s10, s10, 27
	ds_read_b128 v[4:7], v4
	s_waitcnt lgkmcnt(1)
	global_store_dwordx4 v[14:15], v[0:3], off
	s_add_i32 s10, s34, s10
	s_ashr_i32 s10, s10, 5
	v_lshl_add_u64 v[0:1], v[8:9], 0, v[16:17]
	v_lshlrev_b64 v[0:1], 12, v[0:1]
	v_lshl_add_u64 v[0:1], s[26:27], 0, v[0:1]
	s_lshl_b32 s10, s10, 3
	v_readlane_b32 s11, v254, 24
	v_lshl_add_u64 v[0:1], v[0:1], 0, v[12:13]
	s_or_b32 s11, s10, s11
	v_lshl_add_u64 v[0:1], v[0:1], 0, v[128:129]
	s_cmp_gt_i32 s11, 31
	s_waitcnt lgkmcnt(0)
	global_store_dwordx4 v[0:1], v[4:7], off
	s_waitcnt vmcnt(63) expcnt(7) lgkmcnt(15)
	s_barrier
	s_cbranch_scc0 .LBB0_722
